# GEMM K-loops: last-iteration branch resolved before the per-step barrier so the first instruction after the barrier release is an MFMA
# speedup vs baseline: 1.0059x; 1.0031x over previous
.Lg2_150:
	ds_read_b128 v[160:163], v196 offset:1024
	ds_read_b128 v[168:171], v197 offset:1024
	ds_read_b128 v[172:175], v198 offset:1024
	ds_read_b128 v[176:179], v199 offset:1024
	s_waitcnt lgkmcnt(4)
	v_mfma_f32_16x16x32_bf16 v[60:63], v[240:243], v[180:183], v[60:63]
	v_mfma_f32_16x16x32_bf16 v[44:47], v[244:247], v[180:183], v[44:47]
	v_mfma_f32_16x16x32_bf16 v[16:19], v[248:251], v[180:183], v[16:19]
	v_mfma_f32_16x16x32_bf16 v[36:39], v[252:255], v[180:183], v[36:39]
	ds_read_b128 v[180:183], v134 offset:33792
	v_mfma_f32_16x16x32_bf16 v[56:59], v[240:243], v[184:187], v[56:59]
	v_mfma_f32_16x16x32_bf16 v[40:43], v[244:247], v[184:187], v[40:43]
	v_mfma_f32_16x16x32_bf16 v[12:15], v[248:251], v[184:187], v[12:15]
	v_mfma_f32_16x16x32_bf16 v[28:31], v[252:255], v[184:187], v[28:31]
	ds_read_b128 v[184:187], v134 offset:35840
	v_mfma_f32_16x16x32_bf16 v[52:55], v[240:243], v[188:191], v[52:55]
	v_mfma_f32_16x16x32_bf16 v[32:35], v[244:247], v[188:191], v[32:35]
	v_mfma_f32_16x16x32_bf16 v[4:7], v[248:251], v[188:191], v[4:7]
	v_mfma_f32_16x16x32_bf16 v[20:23], v[252:255], v[188:191], v[20:23]
	ds_read_b128 v[188:191], v134 offset:37888
	v_mfma_f32_16x16x32_bf16 v[48:51], v[240:243], v[192:195], v[48:51]
	v_mfma_f32_16x16x32_bf16 v[24:27], v[244:247], v[192:195], v[24:27]
	v_mfma_f32_16x16x32_bf16 v[0:3], v[248:251], v[192:195], v[0:3]
	v_mfma_f32_16x16x32_bf16 v[8:11], v[252:255], v[192:195], v[8:11]
	ds_read_b128 v[192:195], v134 offset:39936
	s_waitcnt lgkmcnt(3)
	v_mfma_f32_16x16x32_bf16 v[124:127], v[160:163], v[180:183], v[124:127]
	v_mfma_f32_16x16x32_bf16 v[108:111], v[168:171], v[180:183], v[108:111]
	v_mfma_f32_16x16x32_bf16 v[92:95], v[172:175], v[180:183], v[92:95]
	v_mfma_f32_16x16x32_bf16 v[76:79], v[176:179], v[180:183], v[76:79]
	ds_read_b128 v[240:243], v200 offset:1024
	ds_read_b128 v[244:247], v201 offset:1024
	s_waitcnt lgkmcnt(4)
	v_mfma_f32_16x16x32_bf16 v[120:123], v[160:163], v[184:187], v[120:123]
	v_mfma_f32_16x16x32_bf16 v[104:107], v[168:171], v[184:187], v[104:107]
	v_mfma_f32_16x16x32_bf16 v[88:91], v[172:175], v[184:187], v[88:91]
	v_mfma_f32_16x16x32_bf16 v[72:75], v[176:179], v[184:187], v[72:75]
	ds_read_b128 v[248:251], v202 offset:1024
	ds_read_b128 v[252:255], v203 offset:1024
	s_waitcnt lgkmcnt(5)
	v_mfma_f32_16x16x32_bf16 v[116:119], v[160:163], v[188:191], v[116:119]
	v_mfma_f32_16x16x32_bf16 v[100:103], v[168:171], v[188:191], v[100:103]
	v_mfma_f32_16x16x32_bf16 v[84:87], v[172:175], v[188:191], v[84:87]
	v_mfma_f32_16x16x32_bf16 v[68:71], v[176:179], v[188:191], v[68:71]
	s_waitcnt lgkmcnt(4)
	v_mfma_f32_16x16x32_bf16 v[112:115], v[160:163], v[192:195], v[112:115]
	v_mfma_f32_16x16x32_bf16 v[96:99], v[168:171], v[192:195], v[96:99]
	v_mfma_f32_16x16x32_bf16 v[80:83], v[172:175], v[192:195], v[80:83]
	v_mfma_f32_16x16x32_bf16 v[64:67], v[176:179], v[192:195], v[64:67]
	s_add_i32 s101, s100, s27
	s_cmpk_eq_i32 s4, 0x700
	s_cbranch_scc1 .Lg4n_150
	s_waitcnt vmcnt(0) lgkmcnt(0)
	s_barrier
	s_add_u32 s98, s98, 0x80
	s_addc_u32 s99, s99, 0
	s_add_u32 vcc_lo, vcc_lo, 0x80
	s_addc_u32 vcc_hi, vcc_hi, 0
	v_mfma_f32_16x16x32_bf16 v[60:63], v[240:243], v[180:183], v[60:63]
	v_mfma_f32_16x16x32_bf16 v[44:47], v[244:247], v[180:183], v[44:47]
	v_mfma_f32_16x16x32_bf16 v[16:19], v[248:251], v[180:183], v[16:19]
	v_mfma_f32_16x16x32_bf16 v[36:39], v[252:255], v[180:183], v[36:39]
	v_add3_u32 v134, s38, v149, v150
	ds_read_b128 v[180:183], v134 offset:32768
	v_add3_u32 v196, s38, v149, v151
	v_add3_u32 v197, s38, v153, v152
	v_add3_u32 v198, s38, v153, v154
	v_add3_u32 v199, s38, v153, v155
	ds_read_b128 v[160:163], v196
	ds_read_b128 v[168:171], v197
	ds_read_b128 v[172:175], v198
	ds_read_b128 v[176:179], v199
	s_mov_b32 m0, s101
	s_nop 0
	global_load_lds_dwordx4 v146, s[98:99]
	v_mfma_f32_16x16x32_bf16 v[56:59], v[240:243], v[184:187], v[56:59]
	v_mfma_f32_16x16x32_bf16 v[40:43], v[244:247], v[184:187], v[40:43]
	v_mfma_f32_16x16x32_bf16 v[12:15], v[248:251], v[184:187], v[12:15]
	v_mfma_f32_16x16x32_bf16 v[28:31], v[252:255], v[184:187], v[28:31]
	ds_read_b128 v[184:187], v134 offset:34816
	v_add3_u32 v200, s38, v153, v156
	v_add3_u32 v201, s38, v153, v157
	v_add3_u32 v202, s38, v153, v158
	v_add3_u32 v203, s38, v153, v159
	s_add_i32 m0, s101, 0x8000
	s_nop 0
	global_load_lds_dwordx4 v138, vcc
	v_mfma_f32_16x16x32_bf16 v[52:55], v[240:243], v[188:191], v[52:55]
	v_mfma_f32_16x16x32_bf16 v[32:35], v[244:247], v[188:191], v[32:35]
	v_mfma_f32_16x16x32_bf16 v[4:7], v[248:251], v[188:191], v[4:7]
	v_mfma_f32_16x16x32_bf16 v[20:23], v[252:255], v[188:191], v[20:23]
	ds_read_b128 v[188:191], v134 offset:36864
	s_add_i32 m0, s101, 0x2000
	s_nop 0
	global_load_lds_dwordx4 v144, s[98:99]
	v_mfma_f32_16x16x32_bf16 v[48:51], v[240:243], v[192:195], v[48:51]
	v_mfma_f32_16x16x32_bf16 v[24:27], v[244:247], v[192:195], v[24:27]
	v_mfma_f32_16x16x32_bf16 v[0:3], v[248:251], v[192:195], v[0:3]
	v_mfma_f32_16x16x32_bf16 v[8:11], v[252:255], v[192:195], v[8:11]
	ds_read_b128 v[192:195], v134 offset:38912
	s_add_i32 m0, s101, 0xa000
	s_nop 0
	global_load_lds_dwordx4 v136, vcc

.Lg4n_150:
	s_waitcnt vmcnt(0) lgkmcnt(0)
	s_barrier
	v_mfma_f32_16x16x32_bf16 v[60:63], v[240:243], v[180:183], v[60:63]
	v_mfma_f32_16x16x32_bf16 v[44:47], v[244:247], v[180:183], v[44:47]
	v_mfma_f32_16x16x32_bf16 v[16:19], v[248:251], v[180:183], v[16:19]
	v_mfma_f32_16x16x32_bf16 v[36:39], v[252:255], v[180:183], v[36:39]
	v_add3_u32 v134, s38, v149, v150
	ds_read_b128 v[180:183], v134 offset:32768
	v_add3_u32 v196, s38, v149, v151
	v_add3_u32 v197, s38, v153, v152
	v_add3_u32 v198, s38, v153, v154
	v_add3_u32 v199, s38, v153, v155
	ds_read_b128 v[160:163], v196
	ds_read_b128 v[168:171], v197
	ds_read_b128 v[172:175], v198
	ds_read_b128 v[176:179], v199
	v_mfma_f32_16x16x32_bf16 v[56:59], v[240:243], v[184:187], v[56:59]
	v_mfma_f32_16x16x32_bf16 v[40:43], v[244:247], v[184:187], v[40:43]
	v_mfma_f32_16x16x32_bf16 v[12:15], v[248:251], v[184:187], v[12:15]
	v_mfma_f32_16x16x32_bf16 v[28:31], v[252:255], v[184:187], v[28:31]
	ds_read_b128 v[184:187], v134 offset:34816
	v_add3_u32 v200, s38, v153, v156
	v_add3_u32 v201, s38, v153, v157
	v_add3_u32 v202, s38, v153, v158
	v_add3_u32 v203, s38, v153, v159
	v_mfma_f32_16x16x32_bf16 v[52:55], v[240:243], v[188:191], v[52:55]
	v_mfma_f32_16x16x32_bf16 v[32:35], v[244:247], v[188:191], v[32:35]
	v_mfma_f32_16x16x32_bf16 v[4:7], v[248:251], v[188:191], v[4:7]
	v_mfma_f32_16x16x32_bf16 v[20:23], v[252:255], v[188:191], v[20:23]
	ds_read_b128 v[188:191], v134 offset:36864
	v_mfma_f32_16x16x32_bf16 v[48:51], v[240:243], v[192:195], v[48:51]
	v_mfma_f32_16x16x32_bf16 v[24:27], v[244:247], v[192:195], v[24:27]
	v_mfma_f32_16x16x32_bf16 v[0:3], v[248:251], v[192:195], v[0:3]
	v_mfma_f32_16x16x32_bf16 v[8:11], v[252:255], v[192:195], v[8:11]
	ds_read_b128 v[192:195], v134 offset:38912
	s_branch .Ltl_150

.Lg2_165:
	ds_read_b128 v[168:171], v162 offset:1024
	ds_read_b128 v[172:175], v163 offset:1024
	ds_read_b128 v[176:179], v200 offset:1024
	ds_read_b128 v[180:183], v201 offset:1024
	s_waitcnt lgkmcnt(4)
	v_mfma_f32_16x16x32_bf16 v[44:47], v[184:187], v[240:243], v[44:47]
	v_mfma_f32_16x16x32_bf16 v[28:31], v[184:187], v[244:247], v[28:31]
	v_mfma_f32_16x16x32_bf16 v[12:15], v[184:187], v[248:251], v[12:15]
	v_mfma_f32_16x16x32_bf16 v[112:115], v[184:187], v[252:255], v[112:115]
	ds_read_b128 v[184:187], v134 offset:33792
	v_mfma_f32_16x16x32_bf16 v[40:43], v[188:191], v[240:243], v[40:43]
	v_mfma_f32_16x16x32_bf16 v[24:27], v[188:191], v[244:247], v[24:27]
	v_mfma_f32_16x16x32_bf16 v[8:11], v[188:191], v[248:251], v[8:11]
	v_mfma_f32_16x16x32_bf16 v[116:119], v[188:191], v[252:255], v[116:119]
	ds_read_b128 v[188:191], v134 offset:35840
	v_mfma_f32_16x16x32_bf16 v[36:39], v[192:195], v[240:243], v[36:39]
	v_mfma_f32_16x16x32_bf16 v[20:23], v[192:195], v[244:247], v[20:23]
	v_mfma_f32_16x16x32_bf16 v[4:7], v[192:195], v[248:251], v[4:7]
	v_mfma_f32_16x16x32_bf16 v[120:123], v[192:195], v[252:255], v[120:123]
	ds_read_b128 v[192:195], v134 offset:37888
	v_mfma_f32_16x16x32_bf16 v[32:35], v[196:199], v[240:243], v[32:35]
	v_mfma_f32_16x16x32_bf16 v[16:19], v[196:199], v[244:247], v[16:19]
	v_mfma_f32_16x16x32_bf16 v[0:3], v[196:199], v[248:251], v[0:3]
	v_mfma_f32_16x16x32_bf16 v[124:127], v[196:199], v[252:255], v[124:127]
	ds_read_b128 v[196:199], v134 offset:39936
	s_waitcnt lgkmcnt(3)
	v_mfma_f32_16x16x32_bf16 v[108:111], v[184:187], v[168:171], v[108:111]
	v_mfma_f32_16x16x32_bf16 v[92:95], v[184:187], v[172:175], v[92:95]
	v_mfma_f32_16x16x32_bf16 v[76:79], v[184:187], v[176:179], v[76:79]
	v_mfma_f32_16x16x32_bf16 v[60:63], v[184:187], v[180:183], v[60:63]
	ds_read_b128 v[240:243], v202 offset:1024
	ds_read_b128 v[244:247], v203 offset:1024
	s_waitcnt lgkmcnt(4)
	v_mfma_f32_16x16x32_bf16 v[104:107], v[188:191], v[168:171], v[104:107]
	v_mfma_f32_16x16x32_bf16 v[88:91], v[188:191], v[172:175], v[88:91]
	v_mfma_f32_16x16x32_bf16 v[72:75], v[188:191], v[176:179], v[72:75]
	v_mfma_f32_16x16x32_bf16 v[56:59], v[188:191], v[180:183], v[56:59]
	ds_read_b128 v[248:251], v204 offset:1024
	ds_read_b128 v[252:255], v205 offset:1024
	s_waitcnt lgkmcnt(5)
	v_mfma_f32_16x16x32_bf16 v[100:103], v[192:195], v[168:171], v[100:103]
	v_mfma_f32_16x16x32_bf16 v[84:87], v[192:195], v[172:175], v[84:87]
	v_mfma_f32_16x16x32_bf16 v[68:71], v[192:195], v[176:179], v[68:71]
	v_mfma_f32_16x16x32_bf16 v[52:55], v[192:195], v[180:183], v[52:55]
	s_waitcnt lgkmcnt(4)
	v_mfma_f32_16x16x32_bf16 v[96:99], v[196:199], v[168:171], v[96:99]
	v_mfma_f32_16x16x32_bf16 v[80:83], v[196:199], v[172:175], v[80:83]
	v_mfma_f32_16x16x32_bf16 v[64:67], v[196:199], v[176:179], v[64:67]
	v_mfma_f32_16x16x32_bf16 v[48:51], v[196:199], v[180:183], v[48:51]
	s_add_i32 s101, s100, s27
	s_cmpk_eq_i32 s30, 0x700
	s_cbranch_scc1 .Lg4n_165
	s_waitcnt vmcnt(0) lgkmcnt(0)
	s_barrier
	s_add_u32 s98, s98, 0x80
	s_addc_u32 s99, s99, 0
	s_add_u32 vcc_lo, vcc_lo, 0x80
	s_addc_u32 vcc_hi, vcc_hi, 0
	v_mfma_f32_16x16x32_bf16 v[44:47], v[184:187], v[240:243], v[44:47]
	v_mfma_f32_16x16x32_bf16 v[28:31], v[184:187], v[244:247], v[28:31]
	v_mfma_f32_16x16x32_bf16 v[12:15], v[184:187], v[248:251], v[12:15]
	v_mfma_f32_16x16x32_bf16 v[112:115], v[184:187], v[252:255], v[112:115]
	v_add3_u32 v134, s34, v151, v152
	ds_read_b128 v[184:187], v134 offset:32768
	v_add3_u32 v162, s34, v151, v153
	v_add3_u32 v163, s34, v155, v154
	v_add3_u32 v200, s34, v155, v156
	v_add3_u32 v201, s34, v155, v157
	ds_read_b128 v[168:171], v162
	ds_read_b128 v[172:175], v163
	ds_read_b128 v[176:179], v200
	ds_read_b128 v[180:183], v201
	s_mov_b32 m0, s101
	s_nop 0
	global_load_lds_dwordx4 v148, s[98:99]
	v_mfma_f32_16x16x32_bf16 v[40:43], v[188:191], v[240:243], v[40:43]
	v_mfma_f32_16x16x32_bf16 v[24:27], v[188:191], v[244:247], v[24:27]
	v_mfma_f32_16x16x32_bf16 v[8:11], v[188:191], v[248:251], v[8:11]
	v_mfma_f32_16x16x32_bf16 v[116:119], v[188:191], v[252:255], v[116:119]
	ds_read_b128 v[188:191], v134 offset:34816
	v_add3_u32 v202, s34, v155, v158
	v_add3_u32 v203, s34, v155, v159
	v_add3_u32 v204, s34, v155, v160
	v_add3_u32 v205, s34, v155, v161
	s_add_i32 m0, s101, 0x8000
	s_nop 0
	global_load_lds_dwordx4 v140, vcc
	v_mfma_f32_16x16x32_bf16 v[36:39], v[192:195], v[240:243], v[36:39]
	v_mfma_f32_16x16x32_bf16 v[20:23], v[192:195], v[244:247], v[20:23]
	v_mfma_f32_16x16x32_bf16 v[4:7], v[192:195], v[248:251], v[4:7]
	v_mfma_f32_16x16x32_bf16 v[120:123], v[192:195], v[252:255], v[120:123]
	ds_read_b128 v[192:195], v134 offset:36864
	s_add_i32 m0, s101, 0x2000
	s_nop 0
	global_load_lds_dwordx4 v146, s[98:99]
	v_mfma_f32_16x16x32_bf16 v[32:35], v[196:199], v[240:243], v[32:35]
	v_mfma_f32_16x16x32_bf16 v[16:19], v[196:199], v[244:247], v[16:19]
	v_mfma_f32_16x16x32_bf16 v[0:3], v[196:199], v[248:251], v[0:3]
	v_mfma_f32_16x16x32_bf16 v[124:127], v[196:199], v[252:255], v[124:127]
	ds_read_b128 v[196:199], v134 offset:38912
	s_add_i32 m0, s101, 0xa000
	s_nop 0
	global_load_lds_dwordx4 v138, vcc

.Lg4n_165:
	s_waitcnt vmcnt(0) lgkmcnt(0)
	s_barrier
	v_mfma_f32_16x16x32_bf16 v[44:47], v[184:187], v[240:243], v[44:47]
	v_mfma_f32_16x16x32_bf16 v[28:31], v[184:187], v[244:247], v[28:31]
	v_mfma_f32_16x16x32_bf16 v[12:15], v[184:187], v[248:251], v[12:15]
	v_mfma_f32_16x16x32_bf16 v[112:115], v[184:187], v[252:255], v[112:115]
	v_add3_u32 v134, s34, v151, v152
	ds_read_b128 v[184:187], v134 offset:32768
	v_add3_u32 v162, s34, v151, v153
	v_add3_u32 v163, s34, v155, v154
	v_add3_u32 v200, s34, v155, v156
	v_add3_u32 v201, s34, v155, v157
	ds_read_b128 v[168:171], v162
	ds_read_b128 v[172:175], v163
	ds_read_b128 v[176:179], v200
	ds_read_b128 v[180:183], v201
	v_mfma_f32_16x16x32_bf16 v[40:43], v[188:191], v[240:243], v[40:43]
	v_mfma_f32_16x16x32_bf16 v[24:27], v[188:191], v[244:247], v[24:27]
	v_mfma_f32_16x16x32_bf16 v[8:11], v[188:191], v[248:251], v[8:11]
	v_mfma_f32_16x16x32_bf16 v[116:119], v[188:191], v[252:255], v[116:119]
	ds_read_b128 v[188:191], v134 offset:34816
	v_add3_u32 v202, s34, v155, v158
	v_add3_u32 v203, s34, v155, v159
	v_add3_u32 v204, s34, v155, v160
	v_add3_u32 v205, s34, v155, v161
	v_mfma_f32_16x16x32_bf16 v[36:39], v[192:195], v[240:243], v[36:39]
	v_mfma_f32_16x16x32_bf16 v[20:23], v[192:195], v[244:247], v[20:23]
	v_mfma_f32_16x16x32_bf16 v[4:7], v[192:195], v[248:251], v[4:7]
	v_mfma_f32_16x16x32_bf16 v[120:123], v[192:195], v[252:255], v[120:123]
	ds_read_b128 v[192:195], v134 offset:36864
	v_mfma_f32_16x16x32_bf16 v[32:35], v[196:199], v[240:243], v[32:35]
	v_mfma_f32_16x16x32_bf16 v[16:19], v[196:199], v[244:247], v[16:19]
	v_mfma_f32_16x16x32_bf16 v[0:3], v[196:199], v[248:251], v[0:3]
	v_mfma_f32_16x16x32_bf16 v[124:127], v[196:199], v[252:255], v[124:127]
	ds_read_b128 v[196:199], v134 offset:38912
	s_branch .Ltl_165

.Lg2_177:
	ds_read_b128 v[160:163], v196 offset:1024
	ds_read_b128 v[168:171], v197 offset:1024
	ds_read_b128 v[172:175], v198 offset:1024
	ds_read_b128 v[176:179], v199 offset:1024
	s_waitcnt lgkmcnt(4)
	v_mfma_f32_16x16x32_bf16 v[44:47], v[240:243], v[180:183], v[44:47]
	v_mfma_f32_16x16x32_bf16 v[28:31], v[244:247], v[180:183], v[28:31]
	v_mfma_f32_16x16x32_bf16 v[12:15], v[248:251], v[180:183], v[12:15]
	v_mfma_f32_16x16x32_bf16 v[112:115], v[252:255], v[180:183], v[112:115]
	ds_read_b128 v[180:183], v134 offset:33792
	v_mfma_f32_16x16x32_bf16 v[40:43], v[240:243], v[184:187], v[40:43]
	v_mfma_f32_16x16x32_bf16 v[24:27], v[244:247], v[184:187], v[24:27]
	v_mfma_f32_16x16x32_bf16 v[8:11], v[248:251], v[184:187], v[8:11]
	v_mfma_f32_16x16x32_bf16 v[116:119], v[252:255], v[184:187], v[116:119]
	ds_read_b128 v[184:187], v134 offset:35840
	v_mfma_f32_16x16x32_bf16 v[36:39], v[240:243], v[188:191], v[36:39]
	v_mfma_f32_16x16x32_bf16 v[20:23], v[244:247], v[188:191], v[20:23]
	v_mfma_f32_16x16x32_bf16 v[4:7], v[248:251], v[188:191], v[4:7]
	v_mfma_f32_16x16x32_bf16 v[120:123], v[252:255], v[188:191], v[120:123]
	ds_read_b128 v[188:191], v134 offset:37888
	v_mfma_f32_16x16x32_bf16 v[32:35], v[240:243], v[192:195], v[32:35]
	v_mfma_f32_16x16x32_bf16 v[16:19], v[244:247], v[192:195], v[16:19]
	v_mfma_f32_16x16x32_bf16 v[0:3], v[248:251], v[192:195], v[0:3]
	v_mfma_f32_16x16x32_bf16 v[124:127], v[252:255], v[192:195], v[124:127]
	ds_read_b128 v[192:195], v134 offset:39936
	s_waitcnt lgkmcnt(3)
	v_mfma_f32_16x16x32_bf16 v[108:111], v[160:163], v[180:183], v[108:111]
	v_mfma_f32_16x16x32_bf16 v[92:95], v[168:171], v[180:183], v[92:95]
	v_mfma_f32_16x16x32_bf16 v[76:79], v[172:175], v[180:183], v[76:79]
	v_mfma_f32_16x16x32_bf16 v[60:63], v[176:179], v[180:183], v[60:63]
	ds_read_b128 v[240:243], v200 offset:1024
	ds_read_b128 v[244:247], v201 offset:1024
	s_waitcnt lgkmcnt(4)
	v_mfma_f32_16x16x32_bf16 v[104:107], v[160:163], v[184:187], v[104:107]
	v_mfma_f32_16x16x32_bf16 v[88:91], v[168:171], v[184:187], v[88:91]
	v_mfma_f32_16x16x32_bf16 v[72:75], v[172:175], v[184:187], v[72:75]
	v_mfma_f32_16x16x32_bf16 v[56:59], v[176:179], v[184:187], v[56:59]
	ds_read_b128 v[248:251], v202 offset:1024
	ds_read_b128 v[252:255], v203 offset:1024
	s_waitcnt lgkmcnt(5)
	v_mfma_f32_16x16x32_bf16 v[100:103], v[160:163], v[188:191], v[100:103]
	v_mfma_f32_16x16x32_bf16 v[84:87], v[168:171], v[188:191], v[84:87]
	v_mfma_f32_16x16x32_bf16 v[68:71], v[172:175], v[188:191], v[68:71]
	v_mfma_f32_16x16x32_bf16 v[52:55], v[176:179], v[188:191], v[52:55]
	s_waitcnt lgkmcnt(4)
	v_mfma_f32_16x16x32_bf16 v[96:99], v[160:163], v[192:195], v[96:99]
	v_mfma_f32_16x16x32_bf16 v[80:83], v[168:171], v[192:195], v[80:83]
	v_mfma_f32_16x16x32_bf16 v[64:67], v[172:175], v[192:195], v[64:67]
	v_mfma_f32_16x16x32_bf16 v[48:51], v[176:179], v[192:195], v[48:51]
	s_add_i32 s101, s100, s27
	s_cmpk_eq_i32 s4, 0x700
	s_cbranch_scc1 .Lg4n_177
	s_waitcnt vmcnt(0) lgkmcnt(0)
	s_barrier
	s_add_u32 s98, s98, 0x80
	s_addc_u32 s99, s99, 0
	s_add_u32 vcc_lo, vcc_lo, 0x80
	s_addc_u32 vcc_hi, vcc_hi, 0
	v_mfma_f32_16x16x32_bf16 v[44:47], v[240:243], v[180:183], v[44:47]
	v_mfma_f32_16x16x32_bf16 v[28:31], v[244:247], v[180:183], v[28:31]
	v_mfma_f32_16x16x32_bf16 v[12:15], v[248:251], v[180:183], v[12:15]
	v_mfma_f32_16x16x32_bf16 v[112:115], v[252:255], v[180:183], v[112:115]
	v_add3_u32 v134, s30, v149, v150
	ds_read_b128 v[180:183], v134 offset:32768
	v_add3_u32 v196, s30, v149, v151
	v_add3_u32 v197, s30, v153, v152
	v_add3_u32 v198, s30, v153, v154
	v_add3_u32 v199, s30, v153, v155
	ds_read_b128 v[160:163], v196
	ds_read_b128 v[168:171], v197
	ds_read_b128 v[172:175], v198
	ds_read_b128 v[176:179], v199
	s_mov_b32 m0, s101
	s_nop 0
	global_load_lds_dwordx4 v146, s[98:99]
	v_mfma_f32_16x16x32_bf16 v[40:43], v[240:243], v[184:187], v[40:43]
	v_mfma_f32_16x16x32_bf16 v[24:27], v[244:247], v[184:187], v[24:27]
	v_mfma_f32_16x16x32_bf16 v[8:11], v[248:251], v[184:187], v[8:11]
	v_mfma_f32_16x16x32_bf16 v[116:119], v[252:255], v[184:187], v[116:119]
	ds_read_b128 v[184:187], v134 offset:34816
	v_add3_u32 v200, s30, v153, v156
	v_add3_u32 v201, s30, v153, v157
	v_add3_u32 v202, s30, v153, v158
	v_add3_u32 v203, s30, v153, v159
	s_add_i32 m0, s101, 0x8000
	s_nop 0
	global_load_lds_dwordx4 v138, vcc
	v_mfma_f32_16x16x32_bf16 v[36:39], v[240:243], v[188:191], v[36:39]
	v_mfma_f32_16x16x32_bf16 v[20:23], v[244:247], v[188:191], v[20:23]
	v_mfma_f32_16x16x32_bf16 v[4:7], v[248:251], v[188:191], v[4:7]
	v_mfma_f32_16x16x32_bf16 v[120:123], v[252:255], v[188:191], v[120:123]
	ds_read_b128 v[188:191], v134 offset:36864
	s_add_i32 m0, s101, 0x2000
	s_nop 0
	global_load_lds_dwordx4 v144, s[98:99]
	v_mfma_f32_16x16x32_bf16 v[32:35], v[240:243], v[192:195], v[32:35]
	v_mfma_f32_16x16x32_bf16 v[16:19], v[244:247], v[192:195], v[16:19]
	v_mfma_f32_16x16x32_bf16 v[0:3], v[248:251], v[192:195], v[0:3]
	v_mfma_f32_16x16x32_bf16 v[124:127], v[252:255], v[192:195], v[124:127]
	ds_read_b128 v[192:195], v134 offset:38912
	s_add_i32 m0, s101, 0xa000
	s_nop 0
	global_load_lds_dwordx4 v136, vcc

.Lg4n_177:
	s_waitcnt vmcnt(0) lgkmcnt(0)
	s_barrier
	v_mfma_f32_16x16x32_bf16 v[44:47], v[240:243], v[180:183], v[44:47]
	v_mfma_f32_16x16x32_bf16 v[28:31], v[244:247], v[180:183], v[28:31]
	v_mfma_f32_16x16x32_bf16 v[12:15], v[248:251], v[180:183], v[12:15]
	v_mfma_f32_16x16x32_bf16 v[112:115], v[252:255], v[180:183], v[112:115]
	v_add3_u32 v134, s30, v149, v150
	ds_read_b128 v[180:183], v134 offset:32768
	v_add3_u32 v196, s30, v149, v151
	v_add3_u32 v197, s30, v153, v152
	v_add3_u32 v198, s30, v153, v154
	v_add3_u32 v199, s30, v153, v155
	ds_read_b128 v[160:163], v196
	ds_read_b128 v[168:171], v197
	ds_read_b128 v[172:175], v198
	ds_read_b128 v[176:179], v199
	v_mfma_f32_16x16x32_bf16 v[40:43], v[240:243], v[184:187], v[40:43]
	v_mfma_f32_16x16x32_bf16 v[24:27], v[244:247], v[184:187], v[24:27]
	v_mfma_f32_16x16x32_bf16 v[8:11], v[248:251], v[184:187], v[8:11]
	v_mfma_f32_16x16x32_bf16 v[116:119], v[252:255], v[184:187], v[116:119]
	ds_read_b128 v[184:187], v134 offset:34816
	v_add3_u32 v200, s30, v153, v156
	v_add3_u32 v201, s30, v153, v157
	v_add3_u32 v202, s30, v153, v158
	v_add3_u32 v203, s30, v153, v159
	v_mfma_f32_16x16x32_bf16 v[36:39], v[240:243], v[188:191], v[36:39]
	v_mfma_f32_16x16x32_bf16 v[20:23], v[244:247], v[188:191], v[20:23]
	v_mfma_f32_16x16x32_bf16 v[4:7], v[248:251], v[188:191], v[4:7]
	v_mfma_f32_16x16x32_bf16 v[120:123], v[252:255], v[188:191], v[120:123]
	ds_read_b128 v[188:191], v134 offset:36864
	v_mfma_f32_16x16x32_bf16 v[32:35], v[240:243], v[192:195], v[32:35]
	v_mfma_f32_16x16x32_bf16 v[16:19], v[244:247], v[192:195], v[16:19]
	v_mfma_f32_16x16x32_bf16 v[0:3], v[248:251], v[192:195], v[0:3]
	v_mfma_f32_16x16x32_bf16 v[124:127], v[252:255], v[192:195], v[124:127]
	ds_read_b128 v[192:195], v134 offset:38912
	s_branch .Ltl_177

.Lg2_181:
	ds_read_b128 v[168:171], v162 offset:1024
	ds_read_b128 v[172:175], v163 offset:1024
	ds_read_b128 v[176:179], v200 offset:1024
	ds_read_b128 v[180:183], v201 offset:1024
	s_waitcnt lgkmcnt(4)
	v_mfma_f32_16x16x32_bf16 v[60:63], v[184:187], v[240:243], v[60:63]
	v_mfma_f32_16x16x32_bf16 v[44:47], v[184:187], v[244:247], v[44:47]
	v_mfma_f32_16x16x32_bf16 v[16:19], v[184:187], v[248:251], v[16:19]
	v_mfma_f32_16x16x32_bf16 v[36:39], v[184:187], v[252:255], v[36:39]
	ds_read_b128 v[184:187], v161 offset:33792
	v_mfma_f32_16x16x32_bf16 v[56:59], v[188:191], v[240:243], v[56:59]
	v_mfma_f32_16x16x32_bf16 v[40:43], v[188:191], v[244:247], v[40:43]
	v_mfma_f32_16x16x32_bf16 v[12:15], v[188:191], v[248:251], v[12:15]
	v_mfma_f32_16x16x32_bf16 v[28:31], v[188:191], v[252:255], v[28:31]
	ds_read_b128 v[188:191], v161 offset:35840
	v_mfma_f32_16x16x32_bf16 v[52:55], v[192:195], v[240:243], v[52:55]
	v_mfma_f32_16x16x32_bf16 v[32:35], v[192:195], v[244:247], v[32:35]
	v_mfma_f32_16x16x32_bf16 v[4:7], v[192:195], v[248:251], v[4:7]
	v_mfma_f32_16x16x32_bf16 v[20:23], v[192:195], v[252:255], v[20:23]
	ds_read_b128 v[192:195], v161 offset:37888
	v_mfma_f32_16x16x32_bf16 v[48:51], v[196:199], v[240:243], v[48:51]
	v_mfma_f32_16x16x32_bf16 v[24:27], v[196:199], v[244:247], v[24:27]
	v_mfma_f32_16x16x32_bf16 v[0:3], v[196:199], v[248:251], v[0:3]
	v_mfma_f32_16x16x32_bf16 v[8:11], v[196:199], v[252:255], v[8:11]
	ds_read_b128 v[196:199], v161 offset:39936
	s_waitcnt lgkmcnt(3)
	v_mfma_f32_16x16x32_bf16 v[124:127], v[184:187], v[168:171], v[124:127]
	v_mfma_f32_16x16x32_bf16 v[108:111], v[184:187], v[172:175], v[108:111]
	v_mfma_f32_16x16x32_bf16 v[92:95], v[184:187], v[176:179], v[92:95]
	v_mfma_f32_16x16x32_bf16 v[76:79], v[184:187], v[180:183], v[76:79]
	ds_read_b128 v[240:243], v202 offset:1024
	ds_read_b128 v[244:247], v203 offset:1024
	s_waitcnt lgkmcnt(4)
	v_mfma_f32_16x16x32_bf16 v[120:123], v[188:191], v[168:171], v[120:123]
	v_mfma_f32_16x16x32_bf16 v[104:107], v[188:191], v[172:175], v[104:107]
	v_mfma_f32_16x16x32_bf16 v[88:91], v[188:191], v[176:179], v[88:91]
	v_mfma_f32_16x16x32_bf16 v[72:75], v[188:191], v[180:183], v[72:75]
	ds_read_b128 v[248:251], v204 offset:1024
	ds_read_b128 v[252:255], v205 offset:1024
	s_waitcnt lgkmcnt(5)
	v_mfma_f32_16x16x32_bf16 v[116:119], v[192:195], v[168:171], v[116:119]
	v_mfma_f32_16x16x32_bf16 v[100:103], v[192:195], v[172:175], v[100:103]
	v_mfma_f32_16x16x32_bf16 v[84:87], v[192:195], v[176:179], v[84:87]
	v_mfma_f32_16x16x32_bf16 v[68:71], v[192:195], v[180:183], v[68:71]
	s_waitcnt lgkmcnt(4)
	v_mfma_f32_16x16x32_bf16 v[112:115], v[196:199], v[168:171], v[112:115]
	v_mfma_f32_16x16x32_bf16 v[96:99], v[196:199], v[172:175], v[96:99]
	v_mfma_f32_16x16x32_bf16 v[80:83], v[196:199], v[176:179], v[80:83]
	v_mfma_f32_16x16x32_bf16 v[64:67], v[196:199], v[180:183], v[64:67]
	s_add_i32 s101, s100, s27
	s_cmpk_eq_i32 s4, 0x700
	s_cbranch_scc1 .Lg4n_181
	s_waitcnt vmcnt(0) lgkmcnt(0)
	s_barrier
	s_add_u32 s98, s98, 0x80
	s_addc_u32 s99, s99, 0
	s_add_u32 vcc_lo, vcc_lo, 0x80
	s_addc_u32 vcc_hi, vcc_hi, 0
	v_mfma_f32_16x16x32_bf16 v[60:63], v[184:187], v[240:243], v[60:63]
	v_mfma_f32_16x16x32_bf16 v[44:47], v[184:187], v[244:247], v[44:47]
	v_mfma_f32_16x16x32_bf16 v[16:19], v[184:187], v[248:251], v[16:19]
	v_mfma_f32_16x16x32_bf16 v[36:39], v[184:187], v[252:255], v[36:39]
	v_add3_u32 v161, s28, v151, v152
	ds_read_b128 v[184:187], v161 offset:32768
	v_add3_u32 v162, s28, v151, v153
	v_add3_u32 v163, s28, v154, v134
	v_add3_u32 v200, s28, v154, v155
	v_add3_u32 v201, s28, v154, v156
	ds_read_b128 v[168:171], v162
	ds_read_b128 v[172:175], v163
	ds_read_b128 v[176:179], v200
	ds_read_b128 v[180:183], v201
	s_mov_b32 m0, s101
	s_nop 0
	global_load_lds_dwordx4 v148, s[98:99]
	v_mfma_f32_16x16x32_bf16 v[56:59], v[188:191], v[240:243], v[56:59]
	v_mfma_f32_16x16x32_bf16 v[40:43], v[188:191], v[244:247], v[40:43]
	v_mfma_f32_16x16x32_bf16 v[12:15], v[188:191], v[248:251], v[12:15]
	v_mfma_f32_16x16x32_bf16 v[28:31], v[188:191], v[252:255], v[28:31]
	ds_read_b128 v[188:191], v161 offset:34816
	v_add3_u32 v202, s28, v154, v157
	v_add3_u32 v203, s28, v154, v158
	v_add3_u32 v204, s28, v154, v159
	v_add3_u32 v205, s28, v154, v160
	s_add_i32 m0, s101, 0x8000
	s_nop 0
	global_load_lds_dwordx4 v140, vcc
	v_mfma_f32_16x16x32_bf16 v[52:55], v[192:195], v[240:243], v[52:55]
	v_mfma_f32_16x16x32_bf16 v[32:35], v[192:195], v[244:247], v[32:35]
	v_mfma_f32_16x16x32_bf16 v[4:7], v[192:195], v[248:251], v[4:7]
	v_mfma_f32_16x16x32_bf16 v[20:23], v[192:195], v[252:255], v[20:23]
	ds_read_b128 v[192:195], v161 offset:36864
	s_add_i32 m0, s101, 0x2000
	s_nop 0
	global_load_lds_dwordx4 v146, s[98:99]
	v_mfma_f32_16x16x32_bf16 v[48:51], v[196:199], v[240:243], v[48:51]
	v_mfma_f32_16x16x32_bf16 v[24:27], v[196:199], v[244:247], v[24:27]
	v_mfma_f32_16x16x32_bf16 v[0:3], v[196:199], v[248:251], v[0:3]
	v_mfma_f32_16x16x32_bf16 v[8:11], v[196:199], v[252:255], v[8:11]
	ds_read_b128 v[196:199], v161 offset:38912
	s_add_i32 m0, s101, 0xa000
	s_nop 0
	global_load_lds_dwordx4 v138, vcc

.Lg4n_181:
	s_waitcnt vmcnt(0) lgkmcnt(0)
	s_barrier
	v_mfma_f32_16x16x32_bf16 v[60:63], v[184:187], v[240:243], v[60:63]
	v_mfma_f32_16x16x32_bf16 v[44:47], v[184:187], v[244:247], v[44:47]
	v_mfma_f32_16x16x32_bf16 v[16:19], v[184:187], v[248:251], v[16:19]
	v_mfma_f32_16x16x32_bf16 v[36:39], v[184:187], v[252:255], v[36:39]
	v_add3_u32 v161, s28, v151, v152
	ds_read_b128 v[184:187], v161 offset:32768
	v_add3_u32 v162, s28, v151, v153
	v_add3_u32 v163, s28, v154, v134
	v_add3_u32 v200, s28, v154, v155
	v_add3_u32 v201, s28, v154, v156
	ds_read_b128 v[168:171], v162
	ds_read_b128 v[172:175], v163
	ds_read_b128 v[176:179], v200
	ds_read_b128 v[180:183], v201
	v_mfma_f32_16x16x32_bf16 v[56:59], v[188:191], v[240:243], v[56:59]
	v_mfma_f32_16x16x32_bf16 v[40:43], v[188:191], v[244:247], v[40:43]
	v_mfma_f32_16x16x32_bf16 v[12:15], v[188:191], v[248:251], v[12:15]
	v_mfma_f32_16x16x32_bf16 v[28:31], v[188:191], v[252:255], v[28:31]
	ds_read_b128 v[188:191], v161 offset:34816
	v_add3_u32 v202, s28, v154, v157
	v_add3_u32 v203, s28, v154, v158
	v_add3_u32 v204, s28, v154, v159
	v_add3_u32 v205, s28, v154, v160
	v_mfma_f32_16x16x32_bf16 v[52:55], v[192:195], v[240:243], v[52:55]
	v_mfma_f32_16x16x32_bf16 v[32:35], v[192:195], v[244:247], v[32:35]
	v_mfma_f32_16x16x32_bf16 v[4:7], v[192:195], v[248:251], v[4:7]
	v_mfma_f32_16x16x32_bf16 v[20:23], v[192:195], v[252:255], v[20:23]
	ds_read_b128 v[192:195], v161 offset:36864
	v_mfma_f32_16x16x32_bf16 v[48:51], v[196:199], v[240:243], v[48:51]
	v_mfma_f32_16x16x32_bf16 v[24:27], v[196:199], v[244:247], v[24:27]
	v_mfma_f32_16x16x32_bf16 v[0:3], v[196:199], v[248:251], v[0:3]
	v_mfma_f32_16x16x32_bf16 v[8:11], v[196:199], v[252:255], v[8:11]
	ds_read_b128 v[196:199], v161 offset:38912
	s_branch .Ltl_181

.Lg2_793:
	ds_read_b128 v[164:167], v163 offset:1024
	ds_read_b128 v[168:171], v196 offset:1024
	ds_read_b128 v[172:175], v197 offset:1024
	ds_read_b128 v[176:179], v198 offset:1024
	s_waitcnt lgkmcnt(4)
	v_mfma_f32_16x16x32_bf16 v[62:65], v[180:183], v[240:243], v[62:65]
	v_mfma_f32_16x16x32_bf16 v[46:49], v[180:183], v[244:247], v[46:49]
	v_mfma_f32_16x16x32_bf16 v[18:21], v[180:183], v[248:251], v[18:21]
	v_mfma_f32_16x16x32_bf16 v[38:41], v[180:183], v[252:255], v[38:41]
	ds_read_b128 v[180:183], v130 offset:33792
	v_mfma_f32_16x16x32_bf16 v[58:61], v[184:187], v[240:243], v[58:61]
	v_mfma_f32_16x16x32_bf16 v[42:45], v[184:187], v[244:247], v[42:45]
	v_mfma_f32_16x16x32_bf16 v[10:13], v[184:187], v[248:251], v[10:13]
	v_mfma_f32_16x16x32_bf16 v[30:33], v[184:187], v[252:255], v[30:33]
	ds_read_b128 v[184:187], v130 offset:35840
	v_mfma_f32_16x16x32_bf16 v[54:57], v[188:191], v[240:243], v[54:57]
	v_mfma_f32_16x16x32_bf16 v[34:37], v[188:191], v[244:247], v[34:37]
	v_mfma_f32_16x16x32_bf16 v[6:9], v[188:191], v[248:251], v[6:9]
	v_mfma_f32_16x16x32_bf16 v[22:25], v[188:191], v[252:255], v[22:25]
	ds_read_b128 v[188:191], v130 offset:37888
	v_mfma_f32_16x16x32_bf16 v[50:53], v[192:195], v[240:243], v[50:53]
	v_mfma_f32_16x16x32_bf16 v[26:29], v[192:195], v[244:247], v[26:29]
	v_mfma_f32_16x16x32_bf16 v[2:5], v[192:195], v[248:251], v[2:5]
	v_mfma_f32_16x16x32_bf16 v[14:17], v[192:195], v[252:255], v[14:17]
	ds_read_b128 v[192:195], v130 offset:39936
	s_waitcnt lgkmcnt(3)
	v_mfma_f32_16x16x32_bf16 v[126:129], v[180:183], v[164:167], v[126:129]
	v_mfma_f32_16x16x32_bf16 v[110:113], v[180:183], v[168:171], v[110:113]
	v_mfma_f32_16x16x32_bf16 v[94:97], v[180:183], v[172:175], v[94:97]
	v_mfma_f32_16x16x32_bf16 v[78:81], v[180:183], v[176:179], v[78:81]
	ds_read_b128 v[240:243], v199 offset:1024
	ds_read_b128 v[244:247], v200 offset:1024
	s_waitcnt lgkmcnt(4)
	v_mfma_f32_16x16x32_bf16 v[122:125], v[184:187], v[164:167], v[122:125]
	v_mfma_f32_16x16x32_bf16 v[106:109], v[184:187], v[168:171], v[106:109]
	v_mfma_f32_16x16x32_bf16 v[90:93], v[184:187], v[172:175], v[90:93]
	v_mfma_f32_16x16x32_bf16 v[74:77], v[184:187], v[176:179], v[74:77]
	ds_read_b128 v[248:251], v201 offset:1024
	ds_read_b128 v[252:255], v202 offset:1024
	s_waitcnt lgkmcnt(5)
	v_mfma_f32_16x16x32_bf16 v[118:121], v[188:191], v[164:167], v[118:121]
	v_mfma_f32_16x16x32_bf16 v[102:105], v[188:191], v[168:171], v[102:105]
	v_mfma_f32_16x16x32_bf16 v[86:89], v[188:191], v[172:175], v[86:89]
	v_mfma_f32_16x16x32_bf16 v[70:73], v[188:191], v[176:179], v[70:73]
	s_waitcnt lgkmcnt(4)
	v_mfma_f32_16x16x32_bf16 v[114:117], v[192:195], v[164:167], v[114:117]
	v_mfma_f32_16x16x32_bf16 v[98:101], v[192:195], v[168:171], v[98:101]
	v_mfma_f32_16x16x32_bf16 v[82:85], v[192:195], v[172:175], v[82:85]
	v_mfma_f32_16x16x32_bf16 v[66:69], v[192:195], v[176:179], v[66:69]
	s_add_i32 s101, s100, s31
	s_cmpk_eq_i32 s38, 0x700
	s_cbranch_scc1 .Lg4n_793
	s_waitcnt vmcnt(0) lgkmcnt(0)
	s_barrier
	s_add_u32 s98, s98, 0x80
	s_addc_u32 s99, s99, 0
	s_add_u32 vcc_lo, vcc_lo, 0x80
	s_addc_u32 vcc_hi, vcc_hi, 0
	v_mfma_f32_16x16x32_bf16 v[62:65], v[180:183], v[240:243], v[62:65]
	v_mfma_f32_16x16x32_bf16 v[46:49], v[180:183], v[244:247], v[46:49]
	v_mfma_f32_16x16x32_bf16 v[18:21], v[180:183], v[248:251], v[18:21]
	v_mfma_f32_16x16x32_bf16 v[38:41], v[180:183], v[252:255], v[38:41]
	v_add3_u32 v130, s42, v152, v153
	ds_read_b128 v[180:183], v130 offset:32768
	v_add3_u32 v163, s42, v152, v154
	v_add3_u32 v196, s42, v156, v155
	v_add3_u32 v197, s42, v156, v157
	v_add3_u32 v198, s42, v156, v158
	ds_read_b128 v[164:167], v163
	ds_read_b128 v[168:171], v196
	ds_read_b128 v[172:175], v197
	ds_read_b128 v[176:179], v198
	s_mov_b32 m0, s101
	s_nop 0
	global_load_lds_dwordx4 v148, s[98:99]
	v_mfma_f32_16x16x32_bf16 v[58:61], v[184:187], v[240:243], v[58:61]
	v_mfma_f32_16x16x32_bf16 v[42:45], v[184:187], v[244:247], v[42:45]
	v_mfma_f32_16x16x32_bf16 v[10:13], v[184:187], v[248:251], v[10:13]
	v_mfma_f32_16x16x32_bf16 v[30:33], v[184:187], v[252:255], v[30:33]
	ds_read_b128 v[184:187], v130 offset:34816
	v_add3_u32 v199, s42, v156, v159
	v_add3_u32 v200, s42, v156, v160
	v_add3_u32 v201, s42, v156, v161
	v_add3_u32 v202, s42, v156, v162
	s_add_i32 m0, s101, 0x8000
	s_nop 0
	global_load_lds_dwordx4 v140, vcc
	v_mfma_f32_16x16x32_bf16 v[54:57], v[188:191], v[240:243], v[54:57]
	v_mfma_f32_16x16x32_bf16 v[34:37], v[188:191], v[244:247], v[34:37]
	v_mfma_f32_16x16x32_bf16 v[6:9], v[188:191], v[248:251], v[6:9]
	v_mfma_f32_16x16x32_bf16 v[22:25], v[188:191], v[252:255], v[22:25]
	ds_read_b128 v[188:191], v130 offset:36864
	s_add_i32 m0, s101, 0x2000
	s_nop 0
	global_load_lds_dwordx4 v146, s[98:99]
	v_mfma_f32_16x16x32_bf16 v[50:53], v[192:195], v[240:243], v[50:53]
	v_mfma_f32_16x16x32_bf16 v[26:29], v[192:195], v[244:247], v[26:29]
	v_mfma_f32_16x16x32_bf16 v[2:5], v[192:195], v[248:251], v[2:5]
	v_mfma_f32_16x16x32_bf16 v[14:17], v[192:195], v[252:255], v[14:17]
	ds_read_b128 v[192:195], v130 offset:38912
	s_add_i32 m0, s101, 0xa000
	s_nop 0
	global_load_lds_dwordx4 v138, vcc

.Lg4n_793:
	s_waitcnt vmcnt(0) lgkmcnt(0)
	s_barrier
	v_mfma_f32_16x16x32_bf16 v[62:65], v[180:183], v[240:243], v[62:65]
	v_mfma_f32_16x16x32_bf16 v[46:49], v[180:183], v[244:247], v[46:49]
	v_mfma_f32_16x16x32_bf16 v[18:21], v[180:183], v[248:251], v[18:21]
	v_mfma_f32_16x16x32_bf16 v[38:41], v[180:183], v[252:255], v[38:41]
	v_add3_u32 v130, s42, v152, v153
	ds_read_b128 v[180:183], v130 offset:32768
	v_add3_u32 v163, s42, v152, v154
	v_add3_u32 v196, s42, v156, v155
	v_add3_u32 v197, s42, v156, v157
	v_add3_u32 v198, s42, v156, v158
	ds_read_b128 v[164:167], v163
	ds_read_b128 v[168:171], v196
	ds_read_b128 v[172:175], v197
	ds_read_b128 v[176:179], v198
	v_mfma_f32_16x16x32_bf16 v[58:61], v[184:187], v[240:243], v[58:61]
	v_mfma_f32_16x16x32_bf16 v[42:45], v[184:187], v[244:247], v[42:45]
	v_mfma_f32_16x16x32_bf16 v[10:13], v[184:187], v[248:251], v[10:13]
	v_mfma_f32_16x16x32_bf16 v[30:33], v[184:187], v[252:255], v[30:33]
	ds_read_b128 v[184:187], v130 offset:34816
	v_add3_u32 v199, s42, v156, v159
	v_add3_u32 v200, s42, v156, v160
	v_add3_u32 v201, s42, v156, v161
	v_add3_u32 v202, s42, v156, v162
	v_mfma_f32_16x16x32_bf16 v[54:57], v[188:191], v[240:243], v[54:57]
	v_mfma_f32_16x16x32_bf16 v[34:37], v[188:191], v[244:247], v[34:37]
	v_mfma_f32_16x16x32_bf16 v[6:9], v[188:191], v[248:251], v[6:9]
	v_mfma_f32_16x16x32_bf16 v[22:25], v[188:191], v[252:255], v[22:25]
	ds_read_b128 v[188:191], v130 offset:36864
	v_mfma_f32_16x16x32_bf16 v[50:53], v[192:195], v[240:243], v[50:53]
	v_mfma_f32_16x16x32_bf16 v[26:29], v[192:195], v[244:247], v[26:29]
	v_mfma_f32_16x16x32_bf16 v[2:5], v[192:195], v[248:251], v[2:5]
	v_mfma_f32_16x16x32_bf16 v[14:17], v[192:195], v[252:255], v[14:17]
	ds_read_b128 v[192:195], v130 offset:38912
	s_branch .Ltl_793

.Lg2_795:
	ds_read_b128 v[164:167], v163 offset:1024
	ds_read_b128 v[168:171], v196 offset:1024
	ds_read_b128 v[172:175], v197 offset:1024
	ds_read_b128 v[176:179], v198 offset:1024
	s_waitcnt lgkmcnt(4)
	v_mfma_f32_16x16x32_bf16 v[60:63], v[180:183], v[240:243], v[60:63]
	v_mfma_f32_16x16x32_bf16 v[44:47], v[180:183], v[244:247], v[44:47]
	v_mfma_f32_16x16x32_bf16 v[16:19], v[180:183], v[248:251], v[16:19]
	v_mfma_f32_16x16x32_bf16 v[36:39], v[180:183], v[252:255], v[36:39]
	ds_read_b128 v[180:183], v130 offset:33792
	v_mfma_f32_16x16x32_bf16 v[56:59], v[184:187], v[240:243], v[56:59]
	v_mfma_f32_16x16x32_bf16 v[40:43], v[184:187], v[244:247], v[40:43]
	v_mfma_f32_16x16x32_bf16 v[12:15], v[184:187], v[248:251], v[12:15]
	v_mfma_f32_16x16x32_bf16 v[28:31], v[184:187], v[252:255], v[28:31]
	ds_read_b128 v[184:187], v130 offset:35840
	v_mfma_f32_16x16x32_bf16 v[52:55], v[188:191], v[240:243], v[52:55]
	v_mfma_f32_16x16x32_bf16 v[32:35], v[188:191], v[244:247], v[32:35]
	v_mfma_f32_16x16x32_bf16 v[4:7], v[188:191], v[248:251], v[4:7]
	v_mfma_f32_16x16x32_bf16 v[20:23], v[188:191], v[252:255], v[20:23]
	ds_read_b128 v[188:191], v130 offset:37888
	v_mfma_f32_16x16x32_bf16 v[48:51], v[192:195], v[240:243], v[48:51]
	v_mfma_f32_16x16x32_bf16 v[24:27], v[192:195], v[244:247], v[24:27]
	v_mfma_f32_16x16x32_bf16 v[0:3], v[192:195], v[248:251], v[0:3]
	v_mfma_f32_16x16x32_bf16 v[8:11], v[192:195], v[252:255], v[8:11]
	ds_read_b128 v[192:195], v130 offset:39936
	s_waitcnt lgkmcnt(3)
	v_mfma_f32_16x16x32_bf16 v[124:127], v[180:183], v[164:167], v[124:127]
	v_mfma_f32_16x16x32_bf16 v[108:111], v[180:183], v[168:171], v[108:111]
	v_mfma_f32_16x16x32_bf16 v[92:95], v[180:183], v[172:175], v[92:95]
	v_mfma_f32_16x16x32_bf16 v[76:79], v[180:183], v[176:179], v[76:79]
	ds_read_b128 v[240:243], v199 offset:1024
	ds_read_b128 v[244:247], v200 offset:1024
	s_waitcnt lgkmcnt(4)
	v_mfma_f32_16x16x32_bf16 v[120:123], v[184:187], v[164:167], v[120:123]
	v_mfma_f32_16x16x32_bf16 v[104:107], v[184:187], v[168:171], v[104:107]
	v_mfma_f32_16x16x32_bf16 v[88:91], v[184:187], v[172:175], v[88:91]
	v_mfma_f32_16x16x32_bf16 v[72:75], v[184:187], v[176:179], v[72:75]
	ds_read_b128 v[248:251], v201 offset:1024
	ds_read_b128 v[252:255], v202 offset:1024
	s_waitcnt lgkmcnt(5)
	v_mfma_f32_16x16x32_bf16 v[116:119], v[188:191], v[164:167], v[116:119]
	v_mfma_f32_16x16x32_bf16 v[100:103], v[188:191], v[168:171], v[100:103]
	v_mfma_f32_16x16x32_bf16 v[84:87], v[188:191], v[172:175], v[84:87]
	v_mfma_f32_16x16x32_bf16 v[68:71], v[188:191], v[176:179], v[68:71]
	s_waitcnt lgkmcnt(4)
	v_mfma_f32_16x16x32_bf16 v[112:115], v[192:195], v[164:167], v[112:115]
	v_mfma_f32_16x16x32_bf16 v[96:99], v[192:195], v[168:171], v[96:99]
	v_mfma_f32_16x16x32_bf16 v[80:83], v[192:195], v[172:175], v[80:83]
	v_mfma_f32_16x16x32_bf16 v[64:67], v[192:195], v[176:179], v[64:67]
	s_add_i32 s101, s100, s0
	s_cmpk_eq_i32 s42, 0x700
	s_cbranch_scc1 .Lg4n_795
	s_waitcnt vmcnt(0) lgkmcnt(0)
	s_barrier
	s_add_u32 s98, s98, 0x80
	s_addc_u32 s99, s99, 0
	s_add_u32 vcc_lo, vcc_lo, 0x80
	s_addc_u32 vcc_hi, vcc_hi, 0
	v_mfma_f32_16x16x32_bf16 v[60:63], v[180:183], v[240:243], v[60:63]
	v_mfma_f32_16x16x32_bf16 v[44:47], v[180:183], v[244:247], v[44:47]
	v_mfma_f32_16x16x32_bf16 v[16:19], v[180:183], v[248:251], v[16:19]
	v_mfma_f32_16x16x32_bf16 v[36:39], v[180:183], v[252:255], v[36:39]
	v_add3_u32 v130, s53, v152, v153
	ds_read_b128 v[180:183], v130 offset:32768
	v_add3_u32 v163, s53, v152, v154
	v_add3_u32 v196, s53, v156, v155
	v_add3_u32 v197, s53, v156, v157
	v_add3_u32 v198, s53, v156, v158
	ds_read_b128 v[164:167], v163
	ds_read_b128 v[168:171], v196
	ds_read_b128 v[172:175], v197
	ds_read_b128 v[176:179], v198
	s_mov_b32 m0, s101
	s_nop 0
	global_load_lds_dwordx4 v148, s[98:99]
	v_mfma_f32_16x16x32_bf16 v[56:59], v[184:187], v[240:243], v[56:59]
	v_mfma_f32_16x16x32_bf16 v[40:43], v[184:187], v[244:247], v[40:43]
	v_mfma_f32_16x16x32_bf16 v[12:15], v[184:187], v[248:251], v[12:15]
	v_mfma_f32_16x16x32_bf16 v[28:31], v[184:187], v[252:255], v[28:31]
	ds_read_b128 v[184:187], v130 offset:34816
	v_add3_u32 v199, s53, v156, v159
	v_add3_u32 v200, s53, v156, v160
	v_add3_u32 v201, s53, v156, v161
	v_add3_u32 v202, s53, v156, v162
	s_add_i32 m0, s101, 0x8000
	s_nop 0
	global_load_lds_dwordx4 v140, vcc
	v_mfma_f32_16x16x32_bf16 v[52:55], v[188:191], v[240:243], v[52:55]
	v_mfma_f32_16x16x32_bf16 v[32:35], v[188:191], v[244:247], v[32:35]
	v_mfma_f32_16x16x32_bf16 v[4:7], v[188:191], v[248:251], v[4:7]
	v_mfma_f32_16x16x32_bf16 v[20:23], v[188:191], v[252:255], v[20:23]
	ds_read_b128 v[188:191], v130 offset:36864
	s_add_i32 m0, s101, 0x2000
	s_nop 0
	global_load_lds_dwordx4 v146, s[98:99]
	v_mfma_f32_16x16x32_bf16 v[48:51], v[192:195], v[240:243], v[48:51]
	v_mfma_f32_16x16x32_bf16 v[24:27], v[192:195], v[244:247], v[24:27]
	v_mfma_f32_16x16x32_bf16 v[0:3], v[192:195], v[248:251], v[0:3]
	v_mfma_f32_16x16x32_bf16 v[8:11], v[192:195], v[252:255], v[8:11]
	ds_read_b128 v[192:195], v130 offset:38912
	s_add_i32 m0, s101, 0xa000
	s_nop 0
	global_load_lds_dwordx4 v138, vcc

.Lg4n_795:
	s_waitcnt vmcnt(0) lgkmcnt(0)
	s_barrier
	v_mfma_f32_16x16x32_bf16 v[60:63], v[180:183], v[240:243], v[60:63]
	v_mfma_f32_16x16x32_bf16 v[44:47], v[180:183], v[244:247], v[44:47]
	v_mfma_f32_16x16x32_bf16 v[16:19], v[180:183], v[248:251], v[16:19]
	v_mfma_f32_16x16x32_bf16 v[36:39], v[180:183], v[252:255], v[36:39]
	v_add3_u32 v130, s53, v152, v153
	ds_read_b128 v[180:183], v130 offset:32768
	v_add3_u32 v163, s53, v152, v154
	v_add3_u32 v196, s53, v156, v155
	v_add3_u32 v197, s53, v156, v157
	v_add3_u32 v198, s53, v156, v158
	ds_read_b128 v[164:167], v163
	ds_read_b128 v[168:171], v196
	ds_read_b128 v[172:175], v197
	ds_read_b128 v[176:179], v198
	v_mfma_f32_16x16x32_bf16 v[56:59], v[184:187], v[240:243], v[56:59]
	v_mfma_f32_16x16x32_bf16 v[40:43], v[184:187], v[244:247], v[40:43]
	v_mfma_f32_16x16x32_bf16 v[12:15], v[184:187], v[248:251], v[12:15]
	v_mfma_f32_16x16x32_bf16 v[28:31], v[184:187], v[252:255], v[28:31]
	ds_read_b128 v[184:187], v130 offset:34816
	v_add3_u32 v199, s53, v156, v159
	v_add3_u32 v200, s53, v156, v160
	v_add3_u32 v201, s53, v156, v161
	v_add3_u32 v202, s53, v156, v162
	v_mfma_f32_16x16x32_bf16 v[52:55], v[188:191], v[240:243], v[52:55]
	v_mfma_f32_16x16x32_bf16 v[32:35], v[188:191], v[244:247], v[32:35]
	v_mfma_f32_16x16x32_bf16 v[4:7], v[188:191], v[248:251], v[4:7]
	v_mfma_f32_16x16x32_bf16 v[20:23], v[188:191], v[252:255], v[20:23]
	ds_read_b128 v[188:191], v130 offset:36864
	v_mfma_f32_16x16x32_bf16 v[48:51], v[192:195], v[240:243], v[48:51]
	v_mfma_f32_16x16x32_bf16 v[24:27], v[192:195], v[244:247], v[24:27]
	v_mfma_f32_16x16x32_bf16 v[0:3], v[192:195], v[248:251], v[0:3]
	v_mfma_f32_16x16x32_bf16 v[8:11], v[192:195], v[252:255], v[8:11]
	ds_read_b128 v[192:195], v130 offset:38912
	s_branch .Ltl_795

.Lg2_797:
	ds_read_b128 v[164:167], v163 offset:1024
	ds_read_b128 v[168:171], v196 offset:1024
	ds_read_b128 v[172:175], v197 offset:1024
	ds_read_b128 v[176:179], v198 offset:1024
	s_waitcnt lgkmcnt(4)
	v_mfma_f32_16x16x32_bf16 v[62:65], v[180:183], v[240:243], v[62:65]
	v_mfma_f32_16x16x32_bf16 v[46:49], v[180:183], v[244:247], v[46:49]
	v_mfma_f32_16x16x32_bf16 v[18:21], v[180:183], v[248:251], v[18:21]
	v_mfma_f32_16x16x32_bf16 v[38:41], v[180:183], v[252:255], v[38:41]
	ds_read_b128 v[180:183], v130 offset:33792
	v_mfma_f32_16x16x32_bf16 v[58:61], v[184:187], v[240:243], v[58:61]
	v_mfma_f32_16x16x32_bf16 v[42:45], v[184:187], v[244:247], v[42:45]
	v_mfma_f32_16x16x32_bf16 v[14:17], v[184:187], v[248:251], v[14:17]
	v_mfma_f32_16x16x32_bf16 v[30:33], v[184:187], v[252:255], v[30:33]
	ds_read_b128 v[184:187], v130 offset:35840
	v_mfma_f32_16x16x32_bf16 v[54:57], v[188:191], v[240:243], v[54:57]
	v_mfma_f32_16x16x32_bf16 v[34:37], v[188:191], v[244:247], v[34:37]
	v_mfma_f32_16x16x32_bf16 v[6:9], v[188:191], v[248:251], v[6:9]
	v_mfma_f32_16x16x32_bf16 v[22:25], v[188:191], v[252:255], v[22:25]
	ds_read_b128 v[188:191], v130 offset:37888
	v_mfma_f32_16x16x32_bf16 v[50:53], v[192:195], v[240:243], v[50:53]
	v_mfma_f32_16x16x32_bf16 v[26:29], v[192:195], v[244:247], v[26:29]
	v_mfma_f32_16x16x32_bf16 v[2:5], v[192:195], v[248:251], v[2:5]
	v_mfma_f32_16x16x32_bf16 v[10:13], v[192:195], v[252:255], v[10:13]
	ds_read_b128 v[192:195], v130 offset:39936
	s_waitcnt lgkmcnt(3)
	v_mfma_f32_16x16x32_bf16 v[126:129], v[180:183], v[164:167], v[126:129]
	v_mfma_f32_16x16x32_bf16 v[110:113], v[180:183], v[168:171], v[110:113]
	v_mfma_f32_16x16x32_bf16 v[94:97], v[180:183], v[172:175], v[94:97]
	v_mfma_f32_16x16x32_bf16 v[78:81], v[180:183], v[176:179], v[78:81]
	ds_read_b128 v[240:243], v199 offset:1024
	ds_read_b128 v[244:247], v200 offset:1024
	s_waitcnt lgkmcnt(4)
	v_mfma_f32_16x16x32_bf16 v[122:125], v[184:187], v[164:167], v[122:125]
	v_mfma_f32_16x16x32_bf16 v[106:109], v[184:187], v[168:171], v[106:109]
	v_mfma_f32_16x16x32_bf16 v[90:93], v[184:187], v[172:175], v[90:93]
	v_mfma_f32_16x16x32_bf16 v[74:77], v[184:187], v[176:179], v[74:77]
	ds_read_b128 v[248:251], v201 offset:1024
	ds_read_b128 v[252:255], v202 offset:1024
	s_waitcnt lgkmcnt(5)
	v_mfma_f32_16x16x32_bf16 v[118:121], v[188:191], v[164:167], v[118:121]
	v_mfma_f32_16x16x32_bf16 v[102:105], v[188:191], v[168:171], v[102:105]
	v_mfma_f32_16x16x32_bf16 v[86:89], v[188:191], v[172:175], v[86:89]
	v_mfma_f32_16x16x32_bf16 v[70:73], v[188:191], v[176:179], v[70:73]
	s_waitcnt lgkmcnt(4)
	v_mfma_f32_16x16x32_bf16 v[114:117], v[192:195], v[164:167], v[114:117]
	v_mfma_f32_16x16x32_bf16 v[98:101], v[192:195], v[168:171], v[98:101]
	v_mfma_f32_16x16x32_bf16 v[82:85], v[192:195], v[172:175], v[82:85]
	v_mfma_f32_16x16x32_bf16 v[66:69], v[192:195], v[176:179], v[66:69]
	s_add_i32 s101, s100, s39
	s_cmpk_eq_i32 s36, 0x700
	s_cbranch_scc1 .Lg4n_797
	s_waitcnt vmcnt(0) lgkmcnt(0)
	s_barrier
	s_add_u32 s98, s98, 0x80
	s_addc_u32 s99, s99, 0
	s_add_u32 vcc_lo, vcc_lo, 0x80
	s_addc_u32 vcc_hi, vcc_hi, 0
	v_mfma_f32_16x16x32_bf16 v[62:65], v[180:183], v[240:243], v[62:65]
	v_mfma_f32_16x16x32_bf16 v[46:49], v[180:183], v[244:247], v[46:49]
	v_mfma_f32_16x16x32_bf16 v[18:21], v[180:183], v[248:251], v[18:21]
	v_mfma_f32_16x16x32_bf16 v[38:41], v[180:183], v[252:255], v[38:41]
	v_add3_u32 v130, s42, v152, v153
	ds_read_b128 v[180:183], v130 offset:32768
	v_add3_u32 v163, s42, v152, v154
	v_add3_u32 v196, s42, v156, v155
	v_add3_u32 v197, s42, v156, v157
	v_add3_u32 v198, s42, v156, v158
	ds_read_b128 v[164:167], v163
	ds_read_b128 v[168:171], v196
	ds_read_b128 v[172:175], v197
	ds_read_b128 v[176:179], v198
	s_mov_b32 m0, s101
	s_nop 0
	global_load_lds_dwordx4 v148, s[98:99]
	v_mfma_f32_16x16x32_bf16 v[58:61], v[184:187], v[240:243], v[58:61]
	v_mfma_f32_16x16x32_bf16 v[42:45], v[184:187], v[244:247], v[42:45]
	v_mfma_f32_16x16x32_bf16 v[14:17], v[184:187], v[248:251], v[14:17]
	v_mfma_f32_16x16x32_bf16 v[30:33], v[184:187], v[252:255], v[30:33]
	ds_read_b128 v[184:187], v130 offset:34816
	v_add3_u32 v199, s42, v156, v159
	v_add3_u32 v200, s42, v156, v160
	v_add3_u32 v201, s42, v156, v161
	v_add3_u32 v202, s42, v156, v162
	s_add_i32 m0, s101, 0x8000
	s_nop 0
	global_load_lds_dwordx4 v140, vcc
	v_mfma_f32_16x16x32_bf16 v[54:57], v[188:191], v[240:243], v[54:57]
	v_mfma_f32_16x16x32_bf16 v[34:37], v[188:191], v[244:247], v[34:37]
	v_mfma_f32_16x16x32_bf16 v[6:9], v[188:191], v[248:251], v[6:9]
	v_mfma_f32_16x16x32_bf16 v[22:25], v[188:191], v[252:255], v[22:25]
	ds_read_b128 v[188:191], v130 offset:36864
	s_add_i32 m0, s101, 0x2000
	s_nop 0
	global_load_lds_dwordx4 v146, s[98:99]
	v_mfma_f32_16x16x32_bf16 v[50:53], v[192:195], v[240:243], v[50:53]
	v_mfma_f32_16x16x32_bf16 v[26:29], v[192:195], v[244:247], v[26:29]
	v_mfma_f32_16x16x32_bf16 v[2:5], v[192:195], v[248:251], v[2:5]
	v_mfma_f32_16x16x32_bf16 v[10:13], v[192:195], v[252:255], v[10:13]
	ds_read_b128 v[192:195], v130 offset:38912
	s_add_i32 m0, s101, 0xa000
	s_nop 0
	global_load_lds_dwordx4 v138, vcc

.Lg4n_797:
	s_waitcnt vmcnt(0) lgkmcnt(0)
	s_barrier
	v_mfma_f32_16x16x32_bf16 v[62:65], v[180:183], v[240:243], v[62:65]
	v_mfma_f32_16x16x32_bf16 v[46:49], v[180:183], v[244:247], v[46:49]
	v_mfma_f32_16x16x32_bf16 v[18:21], v[180:183], v[248:251], v[18:21]
	v_mfma_f32_16x16x32_bf16 v[38:41], v[180:183], v[252:255], v[38:41]
	v_add3_u32 v130, s42, v152, v153
	ds_read_b128 v[180:183], v130 offset:32768
	v_add3_u32 v163, s42, v152, v154
	v_add3_u32 v196, s42, v156, v155
	v_add3_u32 v197, s42, v156, v157
	v_add3_u32 v198, s42, v156, v158
	ds_read_b128 v[164:167], v163
	ds_read_b128 v[168:171], v196
	ds_read_b128 v[172:175], v197
	ds_read_b128 v[176:179], v198
	v_mfma_f32_16x16x32_bf16 v[58:61], v[184:187], v[240:243], v[58:61]
	v_mfma_f32_16x16x32_bf16 v[42:45], v[184:187], v[244:247], v[42:45]
	v_mfma_f32_16x16x32_bf16 v[14:17], v[184:187], v[248:251], v[14:17]
	v_mfma_f32_16x16x32_bf16 v[30:33], v[184:187], v[252:255], v[30:33]
	ds_read_b128 v[184:187], v130 offset:34816
	v_add3_u32 v199, s42, v156, v159
	v_add3_u32 v200, s42, v156, v160
	v_add3_u32 v201, s42, v156, v161
	v_add3_u32 v202, s42, v156, v162
	v_mfma_f32_16x16x32_bf16 v[54:57], v[188:191], v[240:243], v[54:57]
	v_mfma_f32_16x16x32_bf16 v[34:37], v[188:191], v[244:247], v[34:37]
	v_mfma_f32_16x16x32_bf16 v[6:9], v[188:191], v[248:251], v[6:9]
	v_mfma_f32_16x16x32_bf16 v[22:25], v[188:191], v[252:255], v[22:25]
	ds_read_b128 v[188:191], v130 offset:36864
	v_mfma_f32_16x16x32_bf16 v[50:53], v[192:195], v[240:243], v[50:53]
	v_mfma_f32_16x16x32_bf16 v[26:29], v[192:195], v[244:247], v[26:29]
	v_mfma_f32_16x16x32_bf16 v[2:5], v[192:195], v[248:251], v[2:5]
	v_mfma_f32_16x16x32_bf16 v[10:13], v[192:195], v[252:255], v[10:13]
	ds_read_b128 v[192:195], v130 offset:38912
	s_branch .Ltl_797

.Lg2_846:
	ds_read_b128 v[162:165], v161 offset:1024
	ds_read_b128 v[166:169], v194 offset:1024
	ds_read_b128 v[170:173], v195 offset:1024
	ds_read_b128 v[174:177], v196 offset:1024
	s_waitcnt lgkmcnt(4)
	v_mfma_f32_16x16x32_bf16 v[60:63], v[178:181], v[240:243], v[60:63]
	v_mfma_f32_16x16x32_bf16 v[44:47], v[178:181], v[244:247], v[44:47]
	v_mfma_f32_16x16x32_bf16 v[16:19], v[178:181], v[248:251], v[16:19]
	v_mfma_f32_16x16x32_bf16 v[36:39], v[178:181], v[252:255], v[36:39]
	ds_read_b128 v[178:181], v128 offset:33792
	v_mfma_f32_16x16x32_bf16 v[56:59], v[182:185], v[240:243], v[56:59]
	v_mfma_f32_16x16x32_bf16 v[40:43], v[182:185], v[244:247], v[40:43]
	v_mfma_f32_16x16x32_bf16 v[8:11], v[182:185], v[248:251], v[8:11]
	v_mfma_f32_16x16x32_bf16 v[28:31], v[182:185], v[252:255], v[28:31]
	ds_read_b128 v[182:185], v128 offset:35840
	v_mfma_f32_16x16x32_bf16 v[52:55], v[186:189], v[240:243], v[52:55]
	v_mfma_f32_16x16x32_bf16 v[32:35], v[186:189], v[244:247], v[32:35]
	v_mfma_f32_16x16x32_bf16 v[4:7], v[186:189], v[248:251], v[4:7]
	v_mfma_f32_16x16x32_bf16 v[20:23], v[186:189], v[252:255], v[20:23]
	ds_read_b128 v[186:189], v128 offset:37888
	v_mfma_f32_16x16x32_bf16 v[48:51], v[190:193], v[240:243], v[48:51]
	v_mfma_f32_16x16x32_bf16 v[24:27], v[190:193], v[244:247], v[24:27]
	v_mfma_f32_16x16x32_bf16 v[0:3], v[190:193], v[248:251], v[0:3]
	v_mfma_f32_16x16x32_bf16 v[12:15], v[190:193], v[252:255], v[12:15]
	ds_read_b128 v[190:193], v128 offset:39936
	s_waitcnt lgkmcnt(3)
	v_mfma_f32_16x16x32_bf16 v[124:127], v[178:181], v[162:165], v[124:127]
	v_mfma_f32_16x16x32_bf16 v[108:111], v[178:181], v[166:169], v[108:111]
	v_mfma_f32_16x16x32_bf16 v[92:95], v[178:181], v[170:173], v[92:95]
	v_mfma_f32_16x16x32_bf16 v[76:79], v[178:181], v[174:177], v[76:79]
	ds_read_b128 v[240:243], v197 offset:1024
	ds_read_b128 v[244:247], v198 offset:1024
	s_waitcnt lgkmcnt(4)
	v_mfma_f32_16x16x32_bf16 v[120:123], v[182:185], v[162:165], v[120:123]
	v_mfma_f32_16x16x32_bf16 v[104:107], v[182:185], v[166:169], v[104:107]
	v_mfma_f32_16x16x32_bf16 v[88:91], v[182:185], v[170:173], v[88:91]
	v_mfma_f32_16x16x32_bf16 v[72:75], v[182:185], v[174:177], v[72:75]
	ds_read_b128 v[248:251], v199 offset:1024
	ds_read_b128 v[252:255], v200 offset:1024
	s_waitcnt lgkmcnt(5)
	v_mfma_f32_16x16x32_bf16 v[116:119], v[186:189], v[162:165], v[116:119]
	v_mfma_f32_16x16x32_bf16 v[100:103], v[186:189], v[166:169], v[100:103]
	v_mfma_f32_16x16x32_bf16 v[84:87], v[186:189], v[170:173], v[84:87]
	v_mfma_f32_16x16x32_bf16 v[68:71], v[186:189], v[174:177], v[68:71]
	s_waitcnt lgkmcnt(4)
	v_mfma_f32_16x16x32_bf16 v[112:115], v[190:193], v[162:165], v[112:115]
	v_mfma_f32_16x16x32_bf16 v[96:99], v[190:193], v[166:169], v[96:99]
	v_mfma_f32_16x16x32_bf16 v[80:83], v[190:193], v[170:173], v[80:83]
	v_mfma_f32_16x16x32_bf16 v[64:67], v[190:193], v[174:177], v[64:67]
	s_add_i32 s101, s100, s29
	s_cmpk_eq_i32 s16, 0x700
	s_cbranch_scc1 .Lg4n_846
	s_waitcnt vmcnt(0) lgkmcnt(0)
	s_barrier
	s_add_u32 s98, s98, 0x80
	s_addc_u32 s99, s99, 0
	s_add_u32 vcc_lo, vcc_lo, 0x80
	s_addc_u32 vcc_hi, vcc_hi, 0
	v_mfma_f32_16x16x32_bf16 v[60:63], v[178:181], v[240:243], v[60:63]
	v_mfma_f32_16x16x32_bf16 v[44:47], v[178:181], v[244:247], v[44:47]
	v_mfma_f32_16x16x32_bf16 v[16:19], v[178:181], v[248:251], v[16:19]
	v_mfma_f32_16x16x32_bf16 v[36:39], v[178:181], v[252:255], v[36:39]
	v_add3_u32 v128, s30, v150, v151
	ds_read_b128 v[178:181], v128 offset:32768
	v_add3_u32 v161, s30, v150, v152
	v_add3_u32 v194, s30, v154, v153
	v_add3_u32 v195, s30, v154, v155
	v_add3_u32 v196, s30, v154, v156
	ds_read_b128 v[162:165], v161
	ds_read_b128 v[166:169], v194
	ds_read_b128 v[170:173], v195
	ds_read_b128 v[174:177], v196
	s_mov_b32 m0, s101
	s_nop 0
	global_load_lds_dwordx4 v146, s[98:99]
	v_mfma_f32_16x16x32_bf16 v[56:59], v[182:185], v[240:243], v[56:59]
	v_mfma_f32_16x16x32_bf16 v[40:43], v[182:185], v[244:247], v[40:43]
	v_mfma_f32_16x16x32_bf16 v[8:11], v[182:185], v[248:251], v[8:11]
	v_mfma_f32_16x16x32_bf16 v[28:31], v[182:185], v[252:255], v[28:31]
	ds_read_b128 v[182:185], v128 offset:34816
	v_add3_u32 v197, s30, v154, v157
	v_add3_u32 v198, s30, v154, v158
	v_add3_u32 v199, s30, v154, v159
	v_add3_u32 v200, s30, v154, v160
	s_add_i32 m0, s101, 0x8000
	s_nop 0
	global_load_lds_dwordx4 v138, vcc
	v_mfma_f32_16x16x32_bf16 v[52:55], v[186:189], v[240:243], v[52:55]
	v_mfma_f32_16x16x32_bf16 v[32:35], v[186:189], v[244:247], v[32:35]
	v_mfma_f32_16x16x32_bf16 v[4:7], v[186:189], v[248:251], v[4:7]
	v_mfma_f32_16x16x32_bf16 v[20:23], v[186:189], v[252:255], v[20:23]
	ds_read_b128 v[186:189], v128 offset:36864
	s_add_i32 m0, s101, 0x2000
	s_nop 0
	global_load_lds_dwordx4 v144, s[98:99]
	v_mfma_f32_16x16x32_bf16 v[48:51], v[190:193], v[240:243], v[48:51]
	v_mfma_f32_16x16x32_bf16 v[24:27], v[190:193], v[244:247], v[24:27]
	v_mfma_f32_16x16x32_bf16 v[0:3], v[190:193], v[248:251], v[0:3]
	v_mfma_f32_16x16x32_bf16 v[12:15], v[190:193], v[252:255], v[12:15]
	ds_read_b128 v[190:193], v128 offset:38912
	s_add_i32 m0, s101, 0xa000
	s_nop 0
	global_load_lds_dwordx4 v136, vcc

.Lg4n_846:
	s_waitcnt vmcnt(0) lgkmcnt(0)
	s_barrier
	v_mfma_f32_16x16x32_bf16 v[60:63], v[178:181], v[240:243], v[60:63]
	v_mfma_f32_16x16x32_bf16 v[44:47], v[178:181], v[244:247], v[44:47]
	v_mfma_f32_16x16x32_bf16 v[16:19], v[178:181], v[248:251], v[16:19]
	v_mfma_f32_16x16x32_bf16 v[36:39], v[178:181], v[252:255], v[36:39]
	v_add3_u32 v128, s30, v150, v151
	ds_read_b128 v[178:181], v128 offset:32768
	v_add3_u32 v161, s30, v150, v152
	v_add3_u32 v194, s30, v154, v153
	v_add3_u32 v195, s30, v154, v155
	v_add3_u32 v196, s30, v154, v156
	ds_read_b128 v[162:165], v161
	ds_read_b128 v[166:169], v194
	ds_read_b128 v[170:173], v195
	ds_read_b128 v[174:177], v196
	v_mfma_f32_16x16x32_bf16 v[56:59], v[182:185], v[240:243], v[56:59]
	v_mfma_f32_16x16x32_bf16 v[40:43], v[182:185], v[244:247], v[40:43]
	v_mfma_f32_16x16x32_bf16 v[8:11], v[182:185], v[248:251], v[8:11]
	v_mfma_f32_16x16x32_bf16 v[28:31], v[182:185], v[252:255], v[28:31]
	ds_read_b128 v[182:185], v128 offset:34816
	v_add3_u32 v197, s30, v154, v157
	v_add3_u32 v198, s30, v154, v158
	v_add3_u32 v199, s30, v154, v159
	v_add3_u32 v200, s30, v154, v160
	v_mfma_f32_16x16x32_bf16 v[52:55], v[186:189], v[240:243], v[52:55]
	v_mfma_f32_16x16x32_bf16 v[32:35], v[186:189], v[244:247], v[32:35]
	v_mfma_f32_16x16x32_bf16 v[4:7], v[186:189], v[248:251], v[4:7]
	v_mfma_f32_16x16x32_bf16 v[20:23], v[186:189], v[252:255], v[20:23]
	ds_read_b128 v[186:189], v128 offset:36864
	v_mfma_f32_16x16x32_bf16 v[48:51], v[190:193], v[240:243], v[48:51]
	v_mfma_f32_16x16x32_bf16 v[24:27], v[190:193], v[244:247], v[24:27]
	v_mfma_f32_16x16x32_bf16 v[0:3], v[190:193], v[248:251], v[0:3]
	v_mfma_f32_16x16x32_bf16 v[12:15], v[190:193], v[252:255], v[12:15]
	ds_read_b128 v[190:193], v128 offset:38912
	s_branch .Ltl_846

.Lg2_942:
	ds_read_b128 v[162:165], v161 offset:1024
	ds_read_b128 v[166:169], v194 offset:1024
	ds_read_b128 v[170:173], v195 offset:1024
	ds_read_b128 v[174:177], v196 offset:1024
	s_waitcnt lgkmcnt(4)
	v_mfma_f32_16x16x32_bf16 v[44:47], v[178:181], v[240:243], v[44:47]
	v_mfma_f32_16x16x32_bf16 v[28:31], v[178:181], v[244:247], v[28:31]
	v_mfma_f32_16x16x32_bf16 v[12:15], v[178:181], v[248:251], v[12:15]
	v_mfma_f32_16x16x32_bf16 v[112:115], v[178:181], v[252:255], v[112:115]
	ds_read_b128 v[178:181], v128 offset:33792
	v_mfma_f32_16x16x32_bf16 v[40:43], v[182:185], v[240:243], v[40:43]
	v_mfma_f32_16x16x32_bf16 v[24:27], v[182:185], v[244:247], v[24:27]
	v_mfma_f32_16x16x32_bf16 v[8:11], v[182:185], v[248:251], v[8:11]
	v_mfma_f32_16x16x32_bf16 v[116:119], v[182:185], v[252:255], v[116:119]
	ds_read_b128 v[182:185], v128 offset:35840
	v_mfma_f32_16x16x32_bf16 v[36:39], v[186:189], v[240:243], v[36:39]
	v_mfma_f32_16x16x32_bf16 v[20:23], v[186:189], v[244:247], v[20:23]
	v_mfma_f32_16x16x32_bf16 v[4:7], v[186:189], v[248:251], v[4:7]
	v_mfma_f32_16x16x32_bf16 v[120:123], v[186:189], v[252:255], v[120:123]
	ds_read_b128 v[186:189], v128 offset:37888
	v_mfma_f32_16x16x32_bf16 v[32:35], v[190:193], v[240:243], v[32:35]
	v_mfma_f32_16x16x32_bf16 v[16:19], v[190:193], v[244:247], v[16:19]
	v_mfma_f32_16x16x32_bf16 v[0:3], v[190:193], v[248:251], v[0:3]
	v_mfma_f32_16x16x32_bf16 v[124:127], v[190:193], v[252:255], v[124:127]
	ds_read_b128 v[190:193], v128 offset:39936
	s_waitcnt lgkmcnt(3)
	v_mfma_f32_16x16x32_bf16 v[108:111], v[178:181], v[162:165], v[108:111]
	v_mfma_f32_16x16x32_bf16 v[92:95], v[178:181], v[166:169], v[92:95]
	v_mfma_f32_16x16x32_bf16 v[76:79], v[178:181], v[170:173], v[76:79]
	v_mfma_f32_16x16x32_bf16 v[60:63], v[178:181], v[174:177], v[60:63]
	ds_read_b128 v[240:243], v197 offset:1024
	ds_read_b128 v[244:247], v198 offset:1024
	s_waitcnt lgkmcnt(4)
	v_mfma_f32_16x16x32_bf16 v[104:107], v[182:185], v[162:165], v[104:107]
	v_mfma_f32_16x16x32_bf16 v[88:91], v[182:185], v[166:169], v[88:91]
	v_mfma_f32_16x16x32_bf16 v[72:75], v[182:185], v[170:173], v[72:75]
	v_mfma_f32_16x16x32_bf16 v[56:59], v[182:185], v[174:177], v[56:59]
	ds_read_b128 v[248:251], v199 offset:1024
	ds_read_b128 v[252:255], v200 offset:1024
	s_waitcnt lgkmcnt(5)
	v_mfma_f32_16x16x32_bf16 v[100:103], v[186:189], v[162:165], v[100:103]
	v_mfma_f32_16x16x32_bf16 v[84:87], v[186:189], v[166:169], v[84:87]
	v_mfma_f32_16x16x32_bf16 v[68:71], v[186:189], v[170:173], v[68:71]
	v_mfma_f32_16x16x32_bf16 v[52:55], v[186:189], v[174:177], v[52:55]
	s_waitcnt lgkmcnt(4)
	v_mfma_f32_16x16x32_bf16 v[96:99], v[190:193], v[162:165], v[96:99]
	v_mfma_f32_16x16x32_bf16 v[80:83], v[190:193], v[166:169], v[80:83]
	v_mfma_f32_16x16x32_bf16 v[64:67], v[190:193], v[170:173], v[64:67]
	v_mfma_f32_16x16x32_bf16 v[48:51], v[190:193], v[174:177], v[48:51]
	s_add_i32 s101, s100, s17
	s_cmpk_eq_i32 s18, 0x700
	s_cbranch_scc1 .Lg4n_942
	s_waitcnt vmcnt(0) lgkmcnt(0)
	s_barrier
	s_add_u32 s98, s98, 0x80
	s_addc_u32 s99, s99, 0
	s_add_u32 vcc_lo, vcc_lo, 0x80
	s_addc_u32 vcc_hi, vcc_hi, 0
	v_mfma_f32_16x16x32_bf16 v[44:47], v[178:181], v[240:243], v[44:47]
	v_mfma_f32_16x16x32_bf16 v[28:31], v[178:181], v[244:247], v[28:31]
	v_mfma_f32_16x16x32_bf16 v[12:15], v[178:181], v[248:251], v[12:15]
	v_mfma_f32_16x16x32_bf16 v[112:115], v[178:181], v[252:255], v[112:115]
	v_add3_u32 v128, s42, v150, v151
	ds_read_b128 v[178:181], v128 offset:32768
	v_add3_u32 v161, s42, v150, v152
	v_add3_u32 v194, s42, v154, v153
	v_add3_u32 v195, s42, v154, v155
	v_add3_u32 v196, s42, v154, v156
	ds_read_b128 v[162:165], v161
	ds_read_b128 v[166:169], v194
	ds_read_b128 v[170:173], v195
	ds_read_b128 v[174:177], v196
	s_mov_b32 m0, s101
	s_nop 0
	global_load_lds_dwordx4 v146, s[98:99]
	v_mfma_f32_16x16x32_bf16 v[40:43], v[182:185], v[240:243], v[40:43]
	v_mfma_f32_16x16x32_bf16 v[24:27], v[182:185], v[244:247], v[24:27]
	v_mfma_f32_16x16x32_bf16 v[8:11], v[182:185], v[248:251], v[8:11]
	v_mfma_f32_16x16x32_bf16 v[116:119], v[182:185], v[252:255], v[116:119]
	ds_read_b128 v[182:185], v128 offset:34816
	v_add3_u32 v197, s42, v154, v157
	v_add3_u32 v198, s42, v154, v158
	v_add3_u32 v199, s42, v154, v159
	v_add3_u32 v200, s42, v154, v160
	s_add_i32 m0, s101, 0x8000
	s_nop 0
	global_load_lds_dwordx4 v138, vcc
	v_mfma_f32_16x16x32_bf16 v[36:39], v[186:189], v[240:243], v[36:39]
	v_mfma_f32_16x16x32_bf16 v[20:23], v[186:189], v[244:247], v[20:23]
	v_mfma_f32_16x16x32_bf16 v[4:7], v[186:189], v[248:251], v[4:7]
	v_mfma_f32_16x16x32_bf16 v[120:123], v[186:189], v[252:255], v[120:123]
	ds_read_b128 v[186:189], v128 offset:36864
	s_add_i32 m0, s101, 0x2000
	s_nop 0
	global_load_lds_dwordx4 v144, s[98:99]
	v_mfma_f32_16x16x32_bf16 v[32:35], v[190:193], v[240:243], v[32:35]
	v_mfma_f32_16x16x32_bf16 v[16:19], v[190:193], v[244:247], v[16:19]
	v_mfma_f32_16x16x32_bf16 v[0:3], v[190:193], v[248:251], v[0:3]
	v_mfma_f32_16x16x32_bf16 v[124:127], v[190:193], v[252:255], v[124:127]
	ds_read_b128 v[190:193], v128 offset:38912
	s_add_i32 m0, s101, 0xa000
	s_nop 0
	global_load_lds_dwordx4 v136, vcc

.Lg4n_942:
	s_waitcnt vmcnt(0) lgkmcnt(0)
	s_barrier
	v_mfma_f32_16x16x32_bf16 v[44:47], v[178:181], v[240:243], v[44:47]
	v_mfma_f32_16x16x32_bf16 v[28:31], v[178:181], v[244:247], v[28:31]
	v_mfma_f32_16x16x32_bf16 v[12:15], v[178:181], v[248:251], v[12:15]
	v_mfma_f32_16x16x32_bf16 v[112:115], v[178:181], v[252:255], v[112:115]
	v_add3_u32 v128, s42, v150, v151
	ds_read_b128 v[178:181], v128 offset:32768
	v_add3_u32 v161, s42, v150, v152
	v_add3_u32 v194, s42, v154, v153
	v_add3_u32 v195, s42, v154, v155
	v_add3_u32 v196, s42, v154, v156
	ds_read_b128 v[162:165], v161
	ds_read_b128 v[166:169], v194
	ds_read_b128 v[170:173], v195
	ds_read_b128 v[174:177], v196
	v_mfma_f32_16x16x32_bf16 v[40:43], v[182:185], v[240:243], v[40:43]
	v_mfma_f32_16x16x32_bf16 v[24:27], v[182:185], v[244:247], v[24:27]
	v_mfma_f32_16x16x32_bf16 v[8:11], v[182:185], v[248:251], v[8:11]
	v_mfma_f32_16x16x32_bf16 v[116:119], v[182:185], v[252:255], v[116:119]
	ds_read_b128 v[182:185], v128 offset:34816
	v_add3_u32 v197, s42, v154, v157
	v_add3_u32 v198, s42, v154, v158
	v_add3_u32 v199, s42, v154, v159
	v_add3_u32 v200, s42, v154, v160
	v_mfma_f32_16x16x32_bf16 v[36:39], v[186:189], v[240:243], v[36:39]
	v_mfma_f32_16x16x32_bf16 v[20:23], v[186:189], v[244:247], v[20:23]
	v_mfma_f32_16x16x32_bf16 v[4:7], v[186:189], v[248:251], v[4:7]
	v_mfma_f32_16x16x32_bf16 v[120:123], v[186:189], v[252:255], v[120:123]
	ds_read_b128 v[186:189], v128 offset:36864
	v_mfma_f32_16x16x32_bf16 v[32:35], v[190:193], v[240:243], v[32:35]
	v_mfma_f32_16x16x32_bf16 v[16:19], v[190:193], v[244:247], v[16:19]
	v_mfma_f32_16x16x32_bf16 v[0:3], v[190:193], v[248:251], v[0:3]
	v_mfma_f32_16x16x32_bf16 v[124:127], v[190:193], v[252:255], v[124:127]
	ds_read_b128 v[190:193], v128 offset:38912
	s_branch .Ltl_942

.Lg2_1040:
	ds_read_b128 v[162:165], v161 offset:1024
	ds_read_b128 v[166:169], v194 offset:1024
	ds_read_b128 v[170:173], v195 offset:1024
	ds_read_b128 v[174:177], v196 offset:1024
	s_waitcnt lgkmcnt(4)
	v_mfma_f32_16x16x32_bf16 v[44:47], v[178:181], v[240:243], v[44:47]
	v_mfma_f32_16x16x32_bf16 v[28:31], v[178:181], v[244:247], v[28:31]
	v_mfma_f32_16x16x32_bf16 v[12:15], v[178:181], v[248:251], v[12:15]
	v_mfma_f32_16x16x32_bf16 v[112:115], v[178:181], v[252:255], v[112:115]
	ds_read_b128 v[178:181], v128 offset:33792
	v_mfma_f32_16x16x32_bf16 v[40:43], v[182:185], v[240:243], v[40:43]
	v_mfma_f32_16x16x32_bf16 v[24:27], v[182:185], v[244:247], v[24:27]
	v_mfma_f32_16x16x32_bf16 v[8:11], v[182:185], v[248:251], v[8:11]
	v_mfma_f32_16x16x32_bf16 v[116:119], v[182:185], v[252:255], v[116:119]
	ds_read_b128 v[182:185], v128 offset:35840
	v_mfma_f32_16x16x32_bf16 v[36:39], v[186:189], v[240:243], v[36:39]
	v_mfma_f32_16x16x32_bf16 v[20:23], v[186:189], v[244:247], v[20:23]
	v_mfma_f32_16x16x32_bf16 v[4:7], v[186:189], v[248:251], v[4:7]
	v_mfma_f32_16x16x32_bf16 v[120:123], v[186:189], v[252:255], v[120:123]
	ds_read_b128 v[186:189], v128 offset:37888
	v_mfma_f32_16x16x32_bf16 v[32:35], v[190:193], v[240:243], v[32:35]
	v_mfma_f32_16x16x32_bf16 v[16:19], v[190:193], v[244:247], v[16:19]
	v_mfma_f32_16x16x32_bf16 v[0:3], v[190:193], v[248:251], v[0:3]
	v_mfma_f32_16x16x32_bf16 v[124:127], v[190:193], v[252:255], v[124:127]
	ds_read_b128 v[190:193], v128 offset:39936
	s_waitcnt lgkmcnt(3)
	v_mfma_f32_16x16x32_bf16 v[108:111], v[178:181], v[162:165], v[108:111]
	v_mfma_f32_16x16x32_bf16 v[92:95], v[178:181], v[166:169], v[92:95]
	v_mfma_f32_16x16x32_bf16 v[76:79], v[178:181], v[170:173], v[76:79]
	v_mfma_f32_16x16x32_bf16 v[60:63], v[178:181], v[174:177], v[60:63]
	ds_read_b128 v[240:243], v197 offset:1024
	ds_read_b128 v[244:247], v198 offset:1024
	s_waitcnt lgkmcnt(4)
	v_mfma_f32_16x16x32_bf16 v[104:107], v[182:185], v[162:165], v[104:107]
	v_mfma_f32_16x16x32_bf16 v[88:91], v[182:185], v[166:169], v[88:91]
	v_mfma_f32_16x16x32_bf16 v[72:75], v[182:185], v[170:173], v[72:75]
	v_mfma_f32_16x16x32_bf16 v[56:59], v[182:185], v[174:177], v[56:59]
	ds_read_b128 v[248:251], v199 offset:1024
	ds_read_b128 v[252:255], v200 offset:1024
	s_waitcnt lgkmcnt(5)
	v_mfma_f32_16x16x32_bf16 v[100:103], v[186:189], v[162:165], v[100:103]
	v_mfma_f32_16x16x32_bf16 v[84:87], v[186:189], v[166:169], v[84:87]
	v_mfma_f32_16x16x32_bf16 v[68:71], v[186:189], v[170:173], v[68:71]
	v_mfma_f32_16x16x32_bf16 v[52:55], v[186:189], v[174:177], v[52:55]
	s_waitcnt lgkmcnt(4)
	v_mfma_f32_16x16x32_bf16 v[96:99], v[190:193], v[162:165], v[96:99]
	v_mfma_f32_16x16x32_bf16 v[80:83], v[190:193], v[166:169], v[80:83]
	v_mfma_f32_16x16x32_bf16 v[64:67], v[190:193], v[170:173], v[64:67]
	v_mfma_f32_16x16x32_bf16 v[48:51], v[190:193], v[174:177], v[48:51]
	s_add_i32 s101, s100, s17
	s_cmpk_eq_i32 s18, 0x700
	s_cbranch_scc1 .Lg4n_1040
	s_waitcnt vmcnt(0) lgkmcnt(0)
	s_barrier
	s_add_u32 s98, s98, 0x80
	s_addc_u32 s99, s99, 0
	s_add_u32 vcc_lo, vcc_lo, 0x80
	s_addc_u32 vcc_hi, vcc_hi, 0
	v_mfma_f32_16x16x32_bf16 v[44:47], v[178:181], v[240:243], v[44:47]
	v_mfma_f32_16x16x32_bf16 v[28:31], v[178:181], v[244:247], v[28:31]
	v_mfma_f32_16x16x32_bf16 v[12:15], v[178:181], v[248:251], v[12:15]
	v_mfma_f32_16x16x32_bf16 v[112:115], v[178:181], v[252:255], v[112:115]
	v_add3_u32 v128, s43, v150, v151
	ds_read_b128 v[178:181], v128 offset:32768
	v_add3_u32 v161, s43, v150, v152
	v_add3_u32 v194, s43, v154, v153
	v_add3_u32 v195, s43, v154, v155
	v_add3_u32 v196, s43, v154, v156
	ds_read_b128 v[162:165], v161
	ds_read_b128 v[166:169], v194
	ds_read_b128 v[170:173], v195
	ds_read_b128 v[174:177], v196
	s_mov_b32 m0, s101
	s_nop 0
	global_load_lds_dwordx4 v146, s[98:99]
	v_mfma_f32_16x16x32_bf16 v[40:43], v[182:185], v[240:243], v[40:43]
	v_mfma_f32_16x16x32_bf16 v[24:27], v[182:185], v[244:247], v[24:27]
	v_mfma_f32_16x16x32_bf16 v[8:11], v[182:185], v[248:251], v[8:11]
	v_mfma_f32_16x16x32_bf16 v[116:119], v[182:185], v[252:255], v[116:119]
	ds_read_b128 v[182:185], v128 offset:34816
	v_add3_u32 v197, s43, v154, v157
	v_add3_u32 v198, s43, v154, v158
	v_add3_u32 v199, s43, v154, v159
	v_add3_u32 v200, s43, v154, v160
	s_add_i32 m0, s101, 0x8000
	s_nop 0
	global_load_lds_dwordx4 v138, vcc
	v_mfma_f32_16x16x32_bf16 v[36:39], v[186:189], v[240:243], v[36:39]
	v_mfma_f32_16x16x32_bf16 v[20:23], v[186:189], v[244:247], v[20:23]
	v_mfma_f32_16x16x32_bf16 v[4:7], v[186:189], v[248:251], v[4:7]
	v_mfma_f32_16x16x32_bf16 v[120:123], v[186:189], v[252:255], v[120:123]
	ds_read_b128 v[186:189], v128 offset:36864
	s_add_i32 m0, s101, 0x2000
	s_nop 0
	global_load_lds_dwordx4 v144, s[98:99]
	v_mfma_f32_16x16x32_bf16 v[32:35], v[190:193], v[240:243], v[32:35]
	v_mfma_f32_16x16x32_bf16 v[16:19], v[190:193], v[244:247], v[16:19]
	v_mfma_f32_16x16x32_bf16 v[0:3], v[190:193], v[248:251], v[0:3]
	v_mfma_f32_16x16x32_bf16 v[124:127], v[190:193], v[252:255], v[124:127]
	ds_read_b128 v[190:193], v128 offset:38912
	s_add_i32 m0, s101, 0xa000
	s_nop 0
	global_load_lds_dwordx4 v136, vcc

.Lg4n_1040:
	s_waitcnt vmcnt(0) lgkmcnt(0)
	s_barrier
	v_mfma_f32_16x16x32_bf16 v[44:47], v[178:181], v[240:243], v[44:47]
	v_mfma_f32_16x16x32_bf16 v[28:31], v[178:181], v[244:247], v[28:31]
	v_mfma_f32_16x16x32_bf16 v[12:15], v[178:181], v[248:251], v[12:15]
	v_mfma_f32_16x16x32_bf16 v[112:115], v[178:181], v[252:255], v[112:115]
	v_add3_u32 v128, s43, v150, v151
	ds_read_b128 v[178:181], v128 offset:32768
	v_add3_u32 v161, s43, v150, v152
	v_add3_u32 v194, s43, v154, v153
	v_add3_u32 v195, s43, v154, v155
	v_add3_u32 v196, s43, v154, v156
	ds_read_b128 v[162:165], v161
	ds_read_b128 v[166:169], v194
	ds_read_b128 v[170:173], v195
	ds_read_b128 v[174:177], v196
	v_mfma_f32_16x16x32_bf16 v[40:43], v[182:185], v[240:243], v[40:43]
	v_mfma_f32_16x16x32_bf16 v[24:27], v[182:185], v[244:247], v[24:27]
	v_mfma_f32_16x16x32_bf16 v[8:11], v[182:185], v[248:251], v[8:11]
	v_mfma_f32_16x16x32_bf16 v[116:119], v[182:185], v[252:255], v[116:119]
	ds_read_b128 v[182:185], v128 offset:34816
	v_add3_u32 v197, s43, v154, v157
	v_add3_u32 v198, s43, v154, v158
	v_add3_u32 v199, s43, v154, v159
	v_add3_u32 v200, s43, v154, v160
	v_mfma_f32_16x16x32_bf16 v[36:39], v[186:189], v[240:243], v[36:39]
	v_mfma_f32_16x16x32_bf16 v[20:23], v[186:189], v[244:247], v[20:23]
	v_mfma_f32_16x16x32_bf16 v[4:7], v[186:189], v[248:251], v[4:7]
	v_mfma_f32_16x16x32_bf16 v[120:123], v[186:189], v[252:255], v[120:123]
	ds_read_b128 v[186:189], v128 offset:36864
	v_mfma_f32_16x16x32_bf16 v[32:35], v[190:193], v[240:243], v[32:35]
	v_mfma_f32_16x16x32_bf16 v[16:19], v[190:193], v[244:247], v[16:19]
	v_mfma_f32_16x16x32_bf16 v[0:3], v[190:193], v[248:251], v[0:3]
	v_mfma_f32_16x16x32_bf16 v[124:127], v[190:193], v[252:255], v[124:127]
	ds_read_b128 v[190:193], v128 offset:38912
	s_branch .Ltl_1040

.Lg2_1138:
	ds_read_b128 v[162:165], v161 offset:1024
	ds_read_b128 v[166:169], v194 offset:1024
	ds_read_b128 v[170:173], v195 offset:1024
	ds_read_b128 v[174:177], v196 offset:1024
	s_waitcnt lgkmcnt(4)
	v_mfma_f32_16x16x32_bf16 v[60:63], v[178:181], v[240:243], v[60:63]
	v_mfma_f32_16x16x32_bf16 v[44:47], v[178:181], v[244:247], v[44:47]
	v_mfma_f32_16x16x32_bf16 v[16:19], v[178:181], v[248:251], v[16:19]
	v_mfma_f32_16x16x32_bf16 v[36:39], v[178:181], v[252:255], v[36:39]
	ds_read_b128 v[178:181], v128 offset:33792
	v_mfma_f32_16x16x32_bf16 v[56:59], v[182:185], v[240:243], v[56:59]
	v_mfma_f32_16x16x32_bf16 v[40:43], v[182:185], v[244:247], v[40:43]
	v_mfma_f32_16x16x32_bf16 v[8:11], v[182:185], v[248:251], v[8:11]
	v_mfma_f32_16x16x32_bf16 v[28:31], v[182:185], v[252:255], v[28:31]
	ds_read_b128 v[182:185], v128 offset:35840
	v_mfma_f32_16x16x32_bf16 v[52:55], v[186:189], v[240:243], v[52:55]
	v_mfma_f32_16x16x32_bf16 v[32:35], v[186:189], v[244:247], v[32:35]
	v_mfma_f32_16x16x32_bf16 v[4:7], v[186:189], v[248:251], v[4:7]
	v_mfma_f32_16x16x32_bf16 v[20:23], v[186:189], v[252:255], v[20:23]
	ds_read_b128 v[186:189], v128 offset:37888
	v_mfma_f32_16x16x32_bf16 v[48:51], v[190:193], v[240:243], v[48:51]
	v_mfma_f32_16x16x32_bf16 v[24:27], v[190:193], v[244:247], v[24:27]
	v_mfma_f32_16x16x32_bf16 v[0:3], v[190:193], v[248:251], v[0:3]
	v_mfma_f32_16x16x32_bf16 v[12:15], v[190:193], v[252:255], v[12:15]
	ds_read_b128 v[190:193], v128 offset:39936
	s_waitcnt lgkmcnt(3)
	v_mfma_f32_16x16x32_bf16 v[124:127], v[178:181], v[162:165], v[124:127]
	v_mfma_f32_16x16x32_bf16 v[108:111], v[178:181], v[166:169], v[108:111]
	v_mfma_f32_16x16x32_bf16 v[92:95], v[178:181], v[170:173], v[92:95]
	v_mfma_f32_16x16x32_bf16 v[76:79], v[178:181], v[174:177], v[76:79]
	ds_read_b128 v[240:243], v197 offset:1024
	ds_read_b128 v[244:247], v198 offset:1024
	s_waitcnt lgkmcnt(4)
	v_mfma_f32_16x16x32_bf16 v[120:123], v[182:185], v[162:165], v[120:123]
	v_mfma_f32_16x16x32_bf16 v[104:107], v[182:185], v[166:169], v[104:107]
	v_mfma_f32_16x16x32_bf16 v[88:91], v[182:185], v[170:173], v[88:91]
	v_mfma_f32_16x16x32_bf16 v[72:75], v[182:185], v[174:177], v[72:75]
	ds_read_b128 v[248:251], v199 offset:1024
	ds_read_b128 v[252:255], v200 offset:1024
	s_waitcnt lgkmcnt(5)
	v_mfma_f32_16x16x32_bf16 v[116:119], v[186:189], v[162:165], v[116:119]
	v_mfma_f32_16x16x32_bf16 v[100:103], v[186:189], v[166:169], v[100:103]
	v_mfma_f32_16x16x32_bf16 v[84:87], v[186:189], v[170:173], v[84:87]
	v_mfma_f32_16x16x32_bf16 v[68:71], v[186:189], v[174:177], v[68:71]
	s_waitcnt lgkmcnt(4)
	v_mfma_f32_16x16x32_bf16 v[112:115], v[190:193], v[162:165], v[112:115]
	v_mfma_f32_16x16x32_bf16 v[96:99], v[190:193], v[166:169], v[96:99]
	v_mfma_f32_16x16x32_bf16 v[80:83], v[190:193], v[170:173], v[80:83]
	v_mfma_f32_16x16x32_bf16 v[64:67], v[190:193], v[174:177], v[64:67]
	s_add_i32 s101, s100, s27
	s_cmpk_eq_i32 s12, 0x1500
	s_cbranch_scc1 .Lg4n_1138
	s_waitcnt vmcnt(0) lgkmcnt(0)
	s_barrier
	s_add_u32 s98, s98, 0x80
	s_addc_u32 s99, s99, 0
	s_add_u32 vcc_lo, vcc_lo, 0x80
	s_addc_u32 vcc_hi, vcc_hi, 0
	v_mfma_f32_16x16x32_bf16 v[60:63], v[178:181], v[240:243], v[60:63]
	v_mfma_f32_16x16x32_bf16 v[44:47], v[178:181], v[244:247], v[44:47]
	v_mfma_f32_16x16x32_bf16 v[16:19], v[178:181], v[248:251], v[16:19]
	v_mfma_f32_16x16x32_bf16 v[36:39], v[178:181], v[252:255], v[36:39]
	v_add3_u32 v128, s28, v150, v151
	ds_read_b128 v[178:181], v128 offset:32768
	v_add3_u32 v161, s28, v150, v152
	v_add3_u32 v194, s28, v154, v153
	v_add3_u32 v195, s28, v154, v155
	v_add3_u32 v196, s28, v154, v156
	ds_read_b128 v[162:165], v161
	ds_read_b128 v[166:169], v194
	ds_read_b128 v[170:173], v195
	ds_read_b128 v[174:177], v196
	s_mov_b32 m0, s101
	s_nop 0
	global_load_lds_dwordx4 v146, s[98:99]
	v_mfma_f32_16x16x32_bf16 v[56:59], v[182:185], v[240:243], v[56:59]
	v_mfma_f32_16x16x32_bf16 v[40:43], v[182:185], v[244:247], v[40:43]
	v_mfma_f32_16x16x32_bf16 v[8:11], v[182:185], v[248:251], v[8:11]
	v_mfma_f32_16x16x32_bf16 v[28:31], v[182:185], v[252:255], v[28:31]
	ds_read_b128 v[182:185], v128 offset:34816
	v_add3_u32 v197, s28, v154, v157
	v_add3_u32 v198, s28, v154, v158
	v_add3_u32 v199, s28, v154, v159
	v_add3_u32 v200, s28, v154, v160
	s_add_i32 m0, s101, 0x8000
	s_nop 0
	global_load_lds_dwordx4 v138, vcc
	v_mfma_f32_16x16x32_bf16 v[52:55], v[186:189], v[240:243], v[52:55]
	v_mfma_f32_16x16x32_bf16 v[32:35], v[186:189], v[244:247], v[32:35]
	v_mfma_f32_16x16x32_bf16 v[4:7], v[186:189], v[248:251], v[4:7]
	v_mfma_f32_16x16x32_bf16 v[20:23], v[186:189], v[252:255], v[20:23]
	ds_read_b128 v[186:189], v128 offset:36864
	s_add_i32 m0, s101, 0x2000
	s_nop 0
	global_load_lds_dwordx4 v144, s[98:99]
	v_mfma_f32_16x16x32_bf16 v[48:51], v[190:193], v[240:243], v[48:51]
	v_mfma_f32_16x16x32_bf16 v[24:27], v[190:193], v[244:247], v[24:27]
	v_mfma_f32_16x16x32_bf16 v[0:3], v[190:193], v[248:251], v[0:3]
	v_mfma_f32_16x16x32_bf16 v[12:15], v[190:193], v[252:255], v[12:15]
	ds_read_b128 v[190:193], v128 offset:38912
	s_add_i32 m0, s101, 0xa000
	s_nop 0
	global_load_lds_dwordx4 v136, vcc

.Lg4n_1138:
	s_waitcnt vmcnt(0) lgkmcnt(0)
	s_barrier
	v_mfma_f32_16x16x32_bf16 v[60:63], v[178:181], v[240:243], v[60:63]
	v_mfma_f32_16x16x32_bf16 v[44:47], v[178:181], v[244:247], v[44:47]
	v_mfma_f32_16x16x32_bf16 v[16:19], v[178:181], v[248:251], v[16:19]
	v_mfma_f32_16x16x32_bf16 v[36:39], v[178:181], v[252:255], v[36:39]
	v_add3_u32 v128, s28, v150, v151
	ds_read_b128 v[178:181], v128 offset:32768
	v_add3_u32 v161, s28, v150, v152
	v_add3_u32 v194, s28, v154, v153
	v_add3_u32 v195, s28, v154, v155
	v_add3_u32 v196, s28, v154, v156
	ds_read_b128 v[162:165], v161
	ds_read_b128 v[166:169], v194
	ds_read_b128 v[170:173], v195
	ds_read_b128 v[174:177], v196
	v_mfma_f32_16x16x32_bf16 v[56:59], v[182:185], v[240:243], v[56:59]
	v_mfma_f32_16x16x32_bf16 v[40:43], v[182:185], v[244:247], v[40:43]
	v_mfma_f32_16x16x32_bf16 v[8:11], v[182:185], v[248:251], v[8:11]
	v_mfma_f32_16x16x32_bf16 v[28:31], v[182:185], v[252:255], v[28:31]
	ds_read_b128 v[182:185], v128 offset:34816
	v_add3_u32 v197, s28, v154, v157
	v_add3_u32 v198, s28, v154, v158
	v_add3_u32 v199, s28, v154, v159
	v_add3_u32 v200, s28, v154, v160
	v_mfma_f32_16x16x32_bf16 v[52:55], v[186:189], v[240:243], v[52:55]
	v_mfma_f32_16x16x32_bf16 v[32:35], v[186:189], v[244:247], v[32:35]
	v_mfma_f32_16x16x32_bf16 v[4:7], v[186:189], v[248:251], v[4:7]
	v_mfma_f32_16x16x32_bf16 v[20:23], v[186:189], v[252:255], v[20:23]
	ds_read_b128 v[186:189], v128 offset:36864
	v_mfma_f32_16x16x32_bf16 v[48:51], v[190:193], v[240:243], v[48:51]
	v_mfma_f32_16x16x32_bf16 v[24:27], v[190:193], v[244:247], v[24:27]
	v_mfma_f32_16x16x32_bf16 v[0:3], v[190:193], v[248:251], v[0:3]
	v_mfma_f32_16x16x32_bf16 v[12:15], v[190:193], v[252:255], v[12:15]
	ds_read_b128 v[190:193], v128 offset:38912
	s_branch .Ltl_1138
